# stack + removed m0 save/restore around the 54 attention LDS-DMA issues (108 scalar instructions)
# speedup vs baseline: 1.0080x; 1.0057x over previous
; #define WAIT_BAR(N) asm volatile("s_waitcnt vmcnt(" #N ") lgkmcnt(0)\n\ts_barrier":::"memory")
;   #define DMA_K(t,slot) glds16s(Kb+(long)(t)*KVBLK*kp,ksrc,(unsigned)__builtin_amdgcn_readfirstlane(kdst+(slot)))
;   #define DMA_V(t,slot) do{ glds16s(Vb+(long)(t)*KVBLK*vp,vsrc,(unsigned)__builtin_amdgcn_readfirstlane(vdst+(slot))); \
;       if(VH==2) glds16s(Vb+(long)(t)*KVBLK*vp+64,vsrc,(unsigned)__builtin_amdgcn_readfirstlane(vdst+(slot)+8192)); }while(0)
;   #define BIASADD(P0,P1,t) do{ if(HAS_BIAS&&(t)>=tn0&&(t)<tn1){ const lds_f32*bp_=btab+(64*(t)+lanebias); \
;     _Pragma("unroll") for(int r=0;r<16;++r){ P0[r]+=bp_[(r&3)+8*(r>>2)]; P1[r]+=bp_[(r&3)+8*(r>>2)+32]; } } }while(0)
;   #define ROT() do{sv_prev=sv_cur;sv_cur=sv_next;sv_next=(sv_next==2*VSL)?0:sv_next+VSL;}while(0)
;   #define KPRE(tn) do{ const lds_cptr kn_=kp0+(((tn)&3)*KSL); kf[0]=KLD(kn_); kf[1]=KLD(kn_+512); kf[2]=KLD(kn_+2048); kf[3]=KLD(kn_+2560); }while(0)
; template<int VH,bool HAS_BIAS,int MODE> __device__ __forceinline__ void attn_unit2(const bf16*Qb,int qp,const bf16*__restrict__ Kb,int kp,const bf16*__restrict__ Vb,int vp,bf16*Ob,int op,int q0,int NT,const float*relb,char*shm,float lam,const float*subg,float gmul){
;     ...
;   DMA_K(0,0);DMA_V(0,0);DMA_K(1,KSL);
;   bf16x8 qr[4];
;   #pragma unroll
;   for(int d0=0;d0<4;++d0)qr[d0]=*reinterpret_cast<const bf16x8*>(&Qw[(long)r32*qp+d0*16+hi*8]);
;   DMA_K(2,2*KSL);
;   float l_reg=0.f;f32x16 o[2*VH];
;   #pragma unroll
;   for(int d_=0;d_<2*VH;++d_)o[d_]=f32x16{};
;   const f32x16 zero16=f32x16{};
;   f32x16 pA0,pA1,pB0,pB1; bf16x8 kf[4];
;   int sv_prev=0,sv_cur=0,sv_next=VSL;
;     ...
;   if(VH==1){WAIT_BAR(3);}else{WAIT_BAR(4);}
;   qkt(pA0,pA1,shm+LM::L_K,qr,zero16,r32,hi);
;   BIASADD(pA0,pA1,0);
;   _Pragma("unroll") for(int r=0;r<16;++r){pA0[r]=__builtin_amdgcn_exp2f(pA0[r]);pA1[r]=__builtin_amdgcn_exp2f(pA1[r]);}
;   WAIT_BAR(0);
;   DMA_K(3,3*KSL);DMA_V(1,VSL);
;   ROT();
;   KPRE(1);
.LBB0_614:
	s_lshl_b64 s[10:11], s[6:7], 10
	s_lshl_b64 s[8:9], s[6:7], 11
	s_add_u32 s4, s38, s8
	s_addc_u32 s14, s39, s9
	s_lshl_b32 s8, s13, 6
	s_ashr_i32 s9, s8, 31
	s_lshl_b64 s[8:9], s[8:9], 1
	s_add_u32 s15, s4, s8
	s_addc_u32 s14, s14, s9
	s_lshl_b64 s[6:7], s[6:7], 9
	s_add_u32 s4, s33, s6
	s_addc_u32 s13, s46, s7
	s_lshl_b32 s20, s12, 7
	s_add_u32 s12, s4, s20
	s_addc_u32 s13, s13, 0
	s_add_u32 s4, s47, s6
	s_addc_u32 s6, s48, s7
	v_mov_b32_e32 v44, v182
	s_add_u32 s20, s4, s20
	s_addc_u32 s21, s6, 0
	v_readfirstlane_b32 s52, v44
	s_ashr_i32 s4, s52, 6
	s_lshl_b32 s6, s22, 8
	s_lshl_b32 s7, s4, 5
	s_add_i32 s6, s7, s6
	s_ashr_i32 s7, s6, 31
	s_lshl_b64 s[6:7], s[6:7], 11
	s_add_u32 s22, s15, s6
	v_and_b32_e32 v158, 63, v44
	s_addc_u32 s23, s14, s7
	s_lshl_b32 s14, s4, 4
	v_bfe_u32 v0, v44, 2, 4
	v_lshl_add_u32 v169, v158, 9, s14
	v_and_or_b32 v0, s14, 48, v0
	s_ashr_i32 s14, s52, 3
	s_and_b32 s14, s14, 0x7fffffe0
	s_lshl_b32 s54, s4, 10
	s_cmp_lg_u32 0, -1
	v_lshl_add_u32 v0, v0, 8, s14
	v_lshlrev_b32_e32 v160, 3, v44
	s_cselect_b32 s14, 0, 0
	v_and_b32_e32 v165, 24, v160
	s_add_i32 s54, s54, s14
	v_and_b32_e32 v161, 31, v44
	v_or_b32_e32 v0, v0, v165
	s_add_i32 s55, s54, 0x8000
	s_mov_b32 m0, s54
	s_nop 0
	global_load_lds_dwordx4 v169, s[12:13]
	v_bfe_u32 v162, v44, 5, 1
	v_lshlrev_b32_e32 v170, 1, v0
	s_mov_b32 m0, s55
	s_nop 0
	global_load_lds_dwordx4 v170, s[20:21]
	s_add_u32 s34, s12, 0x8000
	v_lshlrev_b32_e32 v0, 11, v161
	s_addc_u32 s35, s13, 0
	s_add_i32 s14, s54, 0x2000
	s_mov_b32 m0, s14
	s_nop 0
	global_load_lds_dwordx4 v169, s[34:35]
	v_lshl_or_b32 v0, v162, 4, v0
	global_load_dwordx4 v[124:127], v0, s[22:23]
	global_load_dwordx4 v[120:123], v0, s[22:23] offset:32
	global_load_dwordx4 v[116:119], v0, s[22:23] offset:64
	global_load_dwordx4 v[112:115], v0, s[22:23] offset:96
	s_add_u32 s22, s12, 0x10000
	v_lshlrev_b32_e32 v0, 10, v162
	v_lshlrev_b32_e32 v1, 4, v161
	s_addc_u32 s23, s13, 0
	s_add_i32 s14, s54, 0x4000
	s_mov_b32 m0, s14
	s_nop 0
	global_load_lds_dwordx4 v169, s[22:23]
	v_add3_u32 v164, 0, v0, v1
	s_waitcnt vmcnt(3) lgkmcnt(0)
	s_barrier
	ds_read_b128 v[0:3], v164
	ds_read_b128 v[16:19], v164 offset:512
	ds_read_b128 v[32:35], v164 offset:2048
	s_add_u32 s22, s12, 0x18000
	s_addc_u32 s23, s13, 0
	s_add_i32 s14, s54, 0x6000
	s_add_u32 s34, s20, 0x8000
	s_addc_u32 s35, s21, 0
	s_add_i32 s61, s53, -5
	v_mov_b32_e32 v168, 0
	s_mov_b32 s57, 1
	s_mov_b32 s65, 5
	s_mov_b32 s64, 0
	s_mov_b32 s66, 0x8000
	s_movk_i32 s56, 0x2000
	s_mov_b64 s[44:45], 0x10000
	s_movk_i32 s63, 0x4000
	s_movk_i32 s60, 0x4000
	s_waitcnt vmcnt(3) lgkmcnt(2)
	v_mfma_f32_32x32x16_bf16 v[0:15], v[0:3], v[124:127], 0
	s_waitcnt vmcnt(2) lgkmcnt(0)
	v_mfma_f32_32x32x16_bf16 v[0:15], v[32:35], v[120:123], v[0:15]
	ds_read_b128 v[32:35], v164 offset:2560
	ds_read_b128 v[36:39], v164 offset:4608
	ds_read_b128 v[40:43], v164 offset:4096
	v_mfma_f32_32x32x16_bf16 v[16:31], v[16:19], v[124:127], 0
	s_waitcnt lgkmcnt(2)
	v_mfma_f32_32x32x16_bf16 v[16:31], v[32:35], v[120:123], v[16:31]
	v_lshlrev_b32_e32 v32, 1, v44
	v_lshlrev_b32_e32 v33, 4, v44
	v_and_b32_e32 v166, 32, v32
	v_and_b32_e32 v32, 0xc0, v33
	v_lshl_or_b32 v163, v162, 8, v32
	v_add_u32_e32 v32, 0, v166
	v_add3_u32 v167, v32, v165, v163
	s_waitcnt vmcnt(1) lgkmcnt(0)
	v_mfma_f32_32x32x16_bf16 v[0:15], v[40:43], v[116:119], v[0:15]
	ds_read_b128 v[32:35], v164 offset:6656
	ds_read_b128 v[40:43], v164 offset:6144
	s_waitcnt vmcnt(0) lgkmcnt(0)
	s_barrier
	s_mov_b32 m0, s14
	s_nop 0
	global_load_lds_dwordx4 v169, s[22:23]
	s_add_i32 s14, s54, 0xa000
	s_mov_b32 m0, s14
	s_nop 0
	global_load_lds_dwordx4 v170, s[34:35]
	ds_read_b128 v[128:131], v164 offset:10752
	ds_read_b128 v[132:135], v164 offset:10240
	ds_read_b128 v[136:139], v164 offset:8704
	ds_read_b128 v[80:83], v164 offset:8192
	s_add_u32 s40, s20, 0x18000
	v_mfma_f32_32x32x16_bf16 v[16:31], v[36:39], v[116:119], v[16:31]
	s_addc_u32 s41, s21, 0
	s_add_u32 s42, s12, 0x28000
	s_addc_u32 s43, s13, 0
	s_waitcnt lgkmcnt(4)
	v_mfma_f32_32x32x16_bf16 v[0:15], v[40:43], v[112:115], v[0:15]
	v_mfma_f32_32x32x16_bf16 v[16:31], v[32:35], v[112:115], v[16:31]
	s_nop 10
	v_exp_f32_e32 v48, v0
	v_exp_f32_e32 v49, v1
	v_exp_f32_e32 v50, v2
	v_exp_f32_e32 v51, v3
	v_exp_f32_e32 v52, v4
	v_exp_f32_e32 v53, v5
	v_exp_f32_e32 v54, v6
	v_exp_f32_e32 v32, v16
	v_exp_f32_e32 v33, v17
	v_exp_f32_e32 v34, v18
	v_exp_f32_e32 v35, v19
	v_exp_f32_e32 v36, v20
	v_exp_f32_e32 v37, v21
	v_exp_f32_e32 v38, v22
	v_exp_f32_e32 v39, v23
	v_exp_f32_e32 v40, v24
	v_exp_f32_e32 v41, v25
	v_exp_f32_e32 v42, v26
	v_exp_f32_e32 v43, v27
	v_exp_f32_e32 v44, v28
	v_exp_f32_e32 v45, v29
	v_exp_f32_e32 v46, v30
	v_exp_f32_e32 v47, v31
	v_exp_f32_e32 v55, v7
	v_exp_f32_e32 v56, v8
	v_exp_f32_e32 v57, v9
	v_exp_f32_e32 v58, v10
	v_exp_f32_e32 v59, v11
	v_exp_f32_e32 v60, v12
	v_exp_f32_e32 v61, v13
	v_exp_f32_e32 v62, v14
	v_exp_f32_e32 v63, v15
	v_mov_b32_e32 v0, 0
	v_mov_b32_e32 v1, v168
	v_mov_b32_e32 v2, v168
	v_mov_b32_e32 v3, v168
	v_mov_b32_e32 v4, v168
	v_mov_b32_e32 v5, v168
	v_mov_b32_e32 v6, v168
	v_mov_b32_e32 v7, v168
	v_mov_b32_e32 v8, v168
	v_mov_b32_e32 v9, v168
	v_mov_b32_e32 v10, v168
	v_mov_b32_e32 v11, v168
	v_mov_b32_e32 v12, v168
	v_mov_b32_e32 v13, v168
	v_mov_b32_e32 v14, v168
	v_mov_b32_e32 v15, v168
	v_mov_b32_e32 v16, 0
	v_mov_b32_e32 v17, v168
	v_mov_b32_e32 v18, v168
	v_mov_b32_e32 v19, v168
	v_mov_b32_e32 v20, v168
	v_mov_b32_e32 v21, v168
	v_mov_b32_e32 v22, v168
	v_mov_b32_e32 v23, v168
	v_mov_b32_e32 v24, v168
	v_mov_b32_e32 v25, v168
	v_mov_b32_e32 v26, v168
	v_mov_b32_e32 v27, v168
	v_mov_b32_e32 v28, v168
	v_mov_b32_e32 v29, v168
	v_mov_b32_e32 v30, v168
	v_mov_b32_e32 v31, v168
.LBB0_615:
	s_mov_b32 s62, s60
	s_mov_b32 s60, s56
	s_mov_b32 s58, s66
	s_mov_b64 s[22:23], s[44:45]
	s_mov_b32 s59, s65
	v_add_u32_e32 v148, s64, v167
	ds_read_b64_tr_b16 v[140:141], v148 offset:32768
	ds_read_b64_tr_b16 v[142:143], v148 offset:33280
	s_add_i32 s14, s63, 0xffffe000
	s_and_b32 s44, s14, 0x6000
	v_add_u32_e32 v96, s44, v164
	s_waitcnt lgkmcnt(2)
	v_mfma_f32_32x32x16_bf16 v[80:95], v[80:83], v[124:127], 0
	v_add_f32_e32 v64, v48, v49
	v_add_f32_e32 v64, v50, v64
	v_add_f32_e32 v64, v51, v64
	v_add_f32_e32 v64, v52, v64
	v_add_f32_e32 v64, v53, v64
	v_cvt_pk_bf16_f32 v108, v48, v49
	v_cvt_pk_bf16_f32 v109, v50, v51
	ds_read_b64_tr_b16 v[48:49], v148 offset:36864
	ds_read_b64_tr_b16 v[50:51], v148 offset:37376
	v_add_f32_e32 v64, v54, v64
	v_add_f32_e32 v64, v55, v64
	v_add_f32_e32 v64, v56, v64
	v_add_f32_e32 v97, v57, v64
	v_cvt_pk_bf16_f32 v110, v52, v53
	v_cvt_pk_bf16_f32 v111, v54, v55
	v_mfma_f32_32x32x16_bf16 v[64:79], v[136:139], v[124:127], 0
	ds_read_b128 v[52:55], v96 offset:4096
	ds_read_b128 v[136:139], v96 offset:4608
	ds_read_b64_tr_b16 v[144:145], v148 offset:33792
	ds_read_b64_tr_b16 v[146:147], v148 offset:34304
	v_mfma_f32_32x32x16_bf16 v[80:95], v[132:135], v[120:123], v[80:95]
	v_add_f32_e32 v97, v58, v97
	v_add_f32_e32 v97, v59, v97
	v_add_f32_e32 v97, v60, v97
	v_add_f32_e32 v97, v61, v97
	v_cvt_pk_bf16_f32 v104, v56, v57
	v_cvt_pk_bf16_f32 v105, v58, v59
	ds_read_b64_tr_b16 v[56:57], v148 offset:37888
	ds_read_b64_tr_b16 v[58:59], v148 offset:38400
	v_add_f32_e32 v97, v62, v97
	v_add_f32_e32 v97, v63, v97
	v_add_f32_e32 v97, v32, v97
	v_add_f32_e32 v97, v33, v97
	v_cvt_pk_bf16_f32 v106, v60, v61
	v_cvt_pk_bf16_f32 v107, v62, v63
	v_mfma_f32_32x32x16_bf16 v[64:79], v[128:131], v[120:123], v[64:79]
	ds_read_b128 v[60:63], v96 offset:6144
	ds_read_b128 v[128:131], v96 offset:6656
	ds_read_b64_tr_b16 v[132:133], v148 offset:34816
	ds_read_b64_tr_b16 v[134:135], v148 offset:35328
	s_waitcnt lgkmcnt(9)
	v_mfma_f32_32x32x16_bf16 v[80:95], v[52:55], v[116:119], v[80:95]
	v_add_f32_e32 v96, v34, v97
	v_add_f32_e32 v96, v35, v96
	v_add_f32_e32 v96, v36, v96
	v_add_f32_e32 v96, v37, v96
	v_cvt_pk_bf16_f32 v100, v32, v33
	v_cvt_pk_bf16_f32 v101, v34, v35
	ds_read_b64_tr_b16 v[32:33], v148 offset:38912
	ds_read_b64_tr_b16 v[34:35], v148 offset:39424
	v_add_f32_e32 v52, v38, v96
	v_add_f32_e32 v52, v39, v52
	v_add_f32_e32 v52, v40, v52
	v_add_f32_e32 v52, v41, v52
	v_cvt_pk_bf16_f32 v102, v36, v37
	v_cvt_pk_bf16_f32 v103, v38, v39
	s_waitcnt lgkmcnt(10)
	v_mfma_f32_32x32x16_bf16 v[64:79], v[136:139], v[116:119], v[64:79]
	ds_read_b64_tr_b16 v[36:37], v148 offset:35840
	ds_read_b64_tr_b16 v[38:39], v148 offset:36352
	s_waitcnt lgkmcnt(7)
	v_mfma_f32_32x32x16_bf16 v[80:95], v[60:63], v[112:115], v[80:95]
	v_add_f32_e32 v52, v42, v52
	v_add_f32_e32 v52, v43, v52
	v_add_f32_e32 v52, v44, v52
	v_add_f32_e32 v52, v45, v52
	v_cvt_pk_bf16_f32 v96, v40, v41
	v_cvt_pk_bf16_f32 v97, v42, v43
	ds_read_b64_tr_b16 v[40:41], v148 offset:39936
	ds_read_b64_tr_b16 v[42:43], v148 offset:40448
	v_add_f32_e32 v52, v46, v52
	v_add_f32_e32 v52, v47, v52
	v_add_f32_e32 v52, 0, v52
	v_cvt_pk_bf16_f32 v98, v44, v45
	v_cvt_pk_bf16_f32 v99, v46, v47
	s_waitcnt lgkmcnt(8)
	v_mfma_f32_32x32x16_bf16 v[64:79], v[128:131], v[112:115], v[64:79]
	s_add_u32 s34, s42, 0xffff8000
	s_addc_u32 s35, s43, -1
	s_add_i32 s64, s63, 0x4000
	s_and_b32 s14, s64, 0x6000
	s_add_i32 s14, s14, s54
	s_mov_b32 m0, s14
	s_nop 0
	global_load_lds_dwordx4 v169, s[34:35]
	s_add_u32 s34, s40, 0xffff8000
	s_addc_u32 s35, s41, -1
	s_add_i32 s14, s62, s55
	s_mov_b32 m0, s14
	s_nop 0
	global_load_lds_dwordx4 v170, s[34:35]
	v_add_f32_e32 v148, v168, v52
	v_mfma_f32_32x32x16_bf16 v[0:15], v[108:111], v[140:143], v[0:15]
	v_exp_f32_e32 v80, v80
	v_exp_f32_e32 v81, v81
	v_exp_f32_e32 v82, v82
	v_exp_f32_e32 v83, v83
	v_mfma_f32_32x32x16_bf16 v[16:31], v[108:111], v[48:51], v[16:31]
	v_exp_f32_e32 v84, v84
	v_exp_f32_e32 v85, v85
	v_exp_f32_e32 v86, v86
	v_exp_f32_e32 v87, v87
	v_mfma_f32_32x32x16_bf16 v[0:15], v[104:107], v[144:147], v[0:15]
	v_exp_f32_e32 v88, v88
	v_exp_f32_e32 v89, v89
	v_exp_f32_e32 v90, v90
	v_exp_f32_e32 v91, v91
	v_mfma_f32_32x32x16_bf16 v[16:31], v[104:107], v[56:59], v[16:31]
	v_exp_f32_e32 v92, v92
	v_exp_f32_e32 v93, v93
	v_exp_f32_e32 v94, v94
	v_exp_f32_e32 v95, v95
	s_and_b32 s14, s63, 0x6000
	v_add_u32_e32 v149, s14, v164
	ds_read_b128 v[44:47], v149
	ds_read_b128 v[128:131], v149 offset:512
	ds_read_b128 v[136:139], v149 offset:2048
	ds_read_b128 v[140:143], v149 offset:2560
	s_waitcnt lgkmcnt(10)
	v_mfma_f32_32x32x16_bf16 v[0:15], v[100:103], v[132:135], v[0:15]
	v_exp_f32_e32 v64, v64
	v_exp_f32_e32 v65, v65
	v_exp_f32_e32 v66, v66
	v_exp_f32_e32 v67, v67
	s_waitcnt lgkmcnt(8)
	v_mfma_f32_32x32x16_bf16 v[16:31], v[100:103], v[32:35], v[16:31]
	v_exp_f32_e32 v68, v68
	v_exp_f32_e32 v69, v69
	v_exp_f32_e32 v70, v70
	v_exp_f32_e32 v71, v71
	s_waitcnt lgkmcnt(6)
	v_mfma_f32_32x32x16_bf16 v[0:15], v[96:99], v[36:39], v[0:15]
	v_exp_f32_e32 v72, v72
	v_exp_f32_e32 v73, v73
	v_exp_f32_e32 v74, v74
	v_exp_f32_e32 v75, v75
	s_waitcnt lgkmcnt(4)
	v_mfma_f32_32x32x16_bf16 v[16:31], v[96:99], v[40:43], v[16:31]
	v_exp_f32_e32 v76, v76
	v_exp_f32_e32 v77, v77
	v_exp_f32_e32 v78, v78
	v_exp_f32_e32 v79, v79
	s_waitcnt vmcnt(2) lgkmcnt(0)
	s_barrier
;   #define RSCALE(t) do{ if(HAS_BIAS&&((t)==tn0||(t)==tn1)){ const float f_=__builtin_amdgcn_exp2f(CREG((t)-1)-CREG(t)); l_reg*=f_; \
;     _Pragma("unroll") for(int d_=0;d_<2*VH;++d_) _Pragma("unroll") for(int r=0;r<16;++r)o[d_][r]*=f_; } }while(0)
;   #define ROT() do{sv_prev=sv_cur;sv_cur=sv_next;sv_next=(sv_next==2*VSL)?0:sv_next+VSL;}while(0)
;   #define WAITFULL() do{ if(VH==1){WAIT_BAR(2);}else{WAIT_BAR(3);} }while(0)
; template<int VH,bool HAS_BIAS,int MODE> __device__ __forceinline__ void attn_unit2(const bf16*Qb,int qp,const bf16*__restrict__ Kb,int kp,const bf16*__restrict__ Vb,int vp,bf16*Ob,int op,int q0,int NT,const float*relb,char*shm,float lam,const float*subg,float gmul){
;     ...
;     STEP(pB0,pB1,pA0,pA1,t,true,true,true);     WAITFULL(); RSCALE(t);   ROT();
;     STEP(pA0,pA1,pB0,pB1,t+1,true,true,true);   WAITFULL(); RSCALE(t+1); ROT();
	s_add_i32 s14, s62, 0x2000
	s_cmpk_lg_i32 s62, 0x4000
	s_cselect_b32 s56, s14, 0
	v_add_u32_e32 v150, s60, v167
	ds_read_b64_tr_b16 v[132:133], v150 offset:32768
	ds_read_b64_tr_b16 v[134:135], v150 offset:33280
	s_waitcnt lgkmcnt(5)
	v_mfma_f32_32x32x16_bf16 v[48:63], v[44:47], v[124:127], 0
	v_add_f32_e32 v32, v80, v81
	v_add_f32_e32 v32, v82, v32
	v_add_f32_e32 v32, v83, v32
	v_add_f32_e32 v32, v84, v32
	v_add_f32_e32 v32, v85, v32
	v_cvt_pk_bf16_f32 v108, v80, v81
	v_cvt_pk_bf16_f32 v109, v82, v83
	ds_read_b64_tr_b16 v[80:81], v150 offset:36864
	ds_read_b64_tr_b16 v[82:83], v150 offset:37376
	v_add_f32_e32 v32, v86, v32
	v_add_f32_e32 v32, v87, v32
	v_add_f32_e32 v32, v88, v32
	v_add_f32_e32 v96, v89, v32
	s_waitcnt lgkmcnt(6)
	v_mfma_f32_32x32x16_bf16 v[32:47], v[128:131], v[124:127], 0
	v_cvt_pk_bf16_f32 v110, v84, v85
	v_cvt_pk_bf16_f32 v111, v86, v87
	ds_read_b128 v[84:87], v149 offset:4096
	ds_read_b128 v[128:131], v149 offset:4608
	ds_read_b64_tr_b16 v[144:145], v150 offset:33792
	ds_read_b64_tr_b16 v[146:147], v150 offset:34304
	s_waitcnt lgkmcnt(9)
	v_mfma_f32_32x32x16_bf16 v[48:63], v[136:139], v[120:123], v[48:63]
	v_add_f32_e32 v96, v90, v96
	v_add_f32_e32 v96, v91, v96
	v_add_f32_e32 v96, v92, v96
	v_add_f32_e32 v96, v93, v96
	v_cvt_pk_bf16_f32 v104, v88, v89
	v_cvt_pk_bf16_f32 v105, v90, v91
	ds_read_b64_tr_b16 v[88:89], v150 offset:37888
	ds_read_b64_tr_b16 v[90:91], v150 offset:38400
	s_waitcnt lgkmcnt(10)
	v_mfma_f32_32x32x16_bf16 v[32:47], v[140:143], v[120:123], v[32:47]
	v_add_f32_e32 v96, v94, v96
	v_add_f32_e32 v96, v95, v96
	v_add_f32_e32 v96, v64, v96
	v_add_f32_e32 v96, v65, v96
	v_cvt_pk_bf16_f32 v106, v92, v93
	v_cvt_pk_bf16_f32 v107, v94, v95
	ds_read_b128 v[92:95], v149 offset:6144
	ds_read_b128 v[136:139], v149 offset:6656
	ds_read_b64_tr_b16 v[140:141], v150 offset:34816
	ds_read_b64_tr_b16 v[142:143], v150 offset:35328
	s_waitcnt lgkmcnt(9)
	v_mfma_f32_32x32x16_bf16 v[48:63], v[84:87], v[116:119], v[48:63]
	v_add_f32_e32 v96, v66, v96
	v_add_f32_e32 v96, v67, v96
	v_add_f32_e32 v96, v68, v96
	v_add_f32_e32 v96, v69, v96
	v_cvt_pk_bf16_f32 v100, v64, v65
	v_cvt_pk_bf16_f32 v101, v66, v67
	ds_read_b64_tr_b16 v[64:65], v150 offset:38912
	ds_read_b64_tr_b16 v[66:67], v150 offset:39424
	s_waitcnt lgkmcnt(10)
	v_mfma_f32_32x32x16_bf16 v[32:47], v[128:131], v[116:119], v[32:47]
	v_add_f32_e32 v84, v70, v96
	v_add_f32_e32 v84, v71, v84
	v_add_f32_e32 v84, v72, v84
	v_add_f32_e32 v84, v73, v84
	v_cvt_pk_bf16_f32 v102, v68, v69
	v_cvt_pk_bf16_f32 v103, v70, v71
	ds_read_b64_tr_b16 v[68:69], v150 offset:35840
	ds_read_b64_tr_b16 v[70:71], v150 offset:36352
	s_waitcnt lgkmcnt(7)
	v_mfma_f32_32x32x16_bf16 v[48:63], v[92:95], v[112:115], v[48:63]
	v_add_f32_e32 v84, v74, v84
	v_add_f32_e32 v84, v75, v84
	v_add_f32_e32 v84, v76, v84
	v_add_f32_e32 v84, v77, v84
	v_cvt_pk_bf16_f32 v96, v72, v73
	v_cvt_pk_bf16_f32 v97, v74, v75
	ds_read_b64_tr_b16 v[72:73], v150 offset:39936
	ds_read_b64_tr_b16 v[74:75], v150 offset:40448
	s_waitcnt lgkmcnt(8)
	v_mfma_f32_32x32x16_bf16 v[32:47], v[136:139], v[112:115], v[32:47]
	v_add_f32_e32 v84, v78, v84
	v_add_f32_e32 v84, v79, v84
	v_add_f32_e32 v84, 0, v84
	v_cvt_pk_bf16_f32 v98, v76, v77
	v_cvt_pk_bf16_f32 v99, v78, v79
	s_add_i32 s14, s44, s54
	s_mov_b32 m0, s14
	s_nop 0
	global_load_lds_dwordx4 v169, s[42:43]
	s_add_i32 s14, s56, s55
	s_mov_b32 m0, s14
	s_nop 0
	global_load_lds_dwordx4 v170, s[40:41]
	v_add_f32_e32 v168, v148, v84
	s_add_i32 s57, s57, 2
	v_mfma_f32_32x32x16_bf16 v[0:15], v[108:111], v[132:135], v[0:15]
	v_exp_f32_e32 v48, v48
	v_exp_f32_e32 v49, v49
	v_exp_f32_e32 v50, v50
	v_exp_f32_e32 v51, v51
	v_mfma_f32_32x32x16_bf16 v[16:31], v[108:111], v[80:83], v[16:31]
	v_exp_f32_e32 v52, v52
	v_exp_f32_e32 v53, v53
	v_exp_f32_e32 v54, v54
	v_exp_f32_e32 v55, v55
	v_mfma_f32_32x32x16_bf16 v[0:15], v[104:107], v[144:147], v[0:15]
	v_exp_f32_e32 v56, v56
	v_exp_f32_e32 v57, v57
	v_exp_f32_e32 v58, v58
	v_exp_f32_e32 v59, v59
	v_mfma_f32_32x32x16_bf16 v[16:31], v[104:107], v[88:91], v[16:31]
	v_exp_f32_e32 v60, v60
	v_exp_f32_e32 v61, v61
	v_exp_f32_e32 v62, v62
	v_exp_f32_e32 v63, v63
	s_add_i32 s14, s63, 0x2000
	s_and_b32 s14, s14, 0x6000
	v_add_u32_e32 v76, s14, v164
	ds_read_b128 v[80:83], v76
	ds_read_b128 v[136:139], v76 offset:512
	ds_read_b128 v[132:135], v76 offset:2048
	ds_read_b128 v[128:131], v76 offset:2560
	s_waitcnt lgkmcnt(10)
	v_mfma_f32_32x32x16_bf16 v[0:15], v[100:103], v[140:143], v[0:15]
	v_exp_f32_e32 v32, v32
	v_exp_f32_e32 v33, v33
	v_exp_f32_e32 v34, v34
	v_exp_f32_e32 v35, v35
	s_waitcnt lgkmcnt(8)
	v_mfma_f32_32x32x16_bf16 v[16:31], v[100:103], v[64:67], v[16:31]
	v_exp_f32_e32 v36, v36
	v_exp_f32_e32 v37, v37
	v_exp_f32_e32 v38, v38
	v_exp_f32_e32 v39, v39
	s_waitcnt lgkmcnt(6)
	v_mfma_f32_32x32x16_bf16 v[0:15], v[96:99], v[68:71], v[0:15]
	v_exp_f32_e32 v40, v40
	v_exp_f32_e32 v41, v41
	v_exp_f32_e32 v42, v42
	v_exp_f32_e32 v43, v43
	s_waitcnt lgkmcnt(4)
	v_mfma_f32_32x32x16_bf16 v[16:31], v[96:99], v[72:75], v[16:31]
	v_exp_f32_e32 v44, v44
	v_exp_f32_e32 v45, v45
	v_exp_f32_e32 v46, v46
	v_exp_f32_e32 v47, v47
	s_add_i32 s14, s56, 0x2000
	s_cmpk_lg_i32 s56, 0x4000
	s_cselect_b32 s60, s14, 0
	s_add_u32 s40, s40, 0x10000
	s_addc_u32 s41, s41, 0
	s_add_u32 s42, s42, 0x10000
	s_addc_u32 s43, s43, 0
	s_addk_i32 s66, 0x4000
	s_waitcnt vmcnt(2) lgkmcnt(0)
	s_barrier
	s_add_u32 s44, s22, 0x10000
	s_addc_u32 s45, s23, 0
	s_add_i32 s65, s65, 2
	s_cmp_ge_u32 s57, s61
	s_mov_b32 s63, s64
	s_mov_b32 s64, s62
	s_cbranch_scc0 .LBB0_615
	s_add_i32 s14, s57, 1
	s_cmp_ge_u32 s14, s53
	s_cbranch_scc1 .LBB0_644
	s_add_i32 s61, s53, -2
;   #define RSCALE(t) do{ if(HAS_BIAS&&((t)==tn0||(t)==tn1)){ const float f_=__builtin_amdgcn_exp2f(CREG((t)-1)-CREG(t)); l_reg*=f_; \
;     _Pragma("unroll") for(int d_=0;d_<2*VH;++d_) _Pragma("unroll") for(int r=0;r<16;++r)o[d_][r]*=f_; } }while(0)
;   #define ROT() do{sv_prev=sv_cur;sv_cur=sv_next;sv_next=(sv_next==2*VSL)?0:sv_next+VSL;}while(0)
;   #define ENDW(tt) do{ if((tt)+3<NT){WAITFULL();} else if((tt)+2<NT){ if(VH==1){WAIT_BAR(1);}else{WAIT_BAR(2);} } else {WAIT_BAR(0);} }while(0)
; template<int VH,bool HAS_BIAS,int MODE> __device__ __forceinline__ void attn_unit2(const bf16*Qb,int qp,const bf16*__restrict__ Kb,int kp,const bf16*__restrict__ Vb,int vp,bf16*Ob,int op,int q0,int NT,const float*relb,char*shm,float lam,const float*subg,float gmul){
;     ...
;   for(;t+1<NT;t+=2){
;     STEP(pB0,pB1,pA0,pA1,t,(t+3<NT),(t+1<NT),(t+1<NT));       ENDW(t);   RSCALE(t);   ROT();
.LBB0_618:
	v_add_u32_e32 v152, s62, v167
	ds_read_b64_tr_b16 v[140:141], v152 offset:32768
	ds_read_b64_tr_b16 v[142:143], v152 offset:33280
	s_add_i32 s14, s58, 0xffffe000
	s_and_b32 s62, s14, 0x6000
	v_add_u32_e32 v96, s62, v164
	s_waitcnt lgkmcnt(5)
	v_mfma_f32_32x32x16_bf16 v[80:95], v[80:83], v[124:127], 0
	v_add_f32_e32 v64, v48, v49
	v_add_f32_e32 v64, v50, v64
	v_add_f32_e32 v64, v51, v64
	v_add_f32_e32 v64, v52, v64
	v_add_f32_e32 v64, v53, v64
	v_cvt_pk_bf16_f32 v108, v48, v49
	v_cvt_pk_bf16_f32 v109, v50, v51
	ds_read_b64_tr_b16 v[144:145], v152 offset:36864
	ds_read_b64_tr_b16 v[146:147], v152 offset:37376
	v_add_f32_e32 v48, v54, v64
	s_waitcnt lgkmcnt(6)
	v_mfma_f32_32x32x16_bf16 v[64:79], v[136:139], v[124:127], 0
	v_add_f32_e32 v48, v55, v48
	v_add_f32_e32 v48, v56, v48
	v_add_f32_e32 v97, v57, v48
	v_cvt_pk_bf16_f32 v110, v52, v53
	v_cvt_pk_bf16_f32 v111, v54, v55
	ds_read_b128 v[48:51], v96 offset:4096
	ds_read_b128 v[148:151], v96 offset:4608
	ds_read_b64_tr_b16 v[136:137], v152 offset:33792
	ds_read_b64_tr_b16 v[138:139], v152 offset:34304
	s_waitcnt lgkmcnt(9)
	v_mfma_f32_32x32x16_bf16 v[80:95], v[132:135], v[120:123], v[80:95]
	v_add_f32_e32 v52, v58, v97
	v_add_f32_e32 v52, v59, v52
	v_add_f32_e32 v52, v60, v52
	v_add_f32_e32 v52, v61, v52
	v_cvt_pk_bf16_f32 v104, v56, v57
	v_cvt_pk_bf16_f32 v105, v58, v59
	ds_read_b64_tr_b16 v[56:57], v152 offset:37888
	ds_read_b64_tr_b16 v[58:59], v152 offset:38400
	s_waitcnt lgkmcnt(10)
	v_mfma_f32_32x32x16_bf16 v[64:79], v[128:131], v[120:123], v[64:79]
	v_add_f32_e32 v52, v62, v52
	v_add_f32_e32 v52, v63, v52
	v_add_f32_e32 v52, v32, v52
	v_add_f32_e32 v97, v33, v52
	v_cvt_pk_bf16_f32 v106, v60, v61
	v_cvt_pk_bf16_f32 v107, v62, v63
	ds_read_b128 v[60:63], v96 offset:6144
	ds_read_b128 v[128:131], v96 offset:6656
	ds_read_b64_tr_b16 v[52:53], v152 offset:34816
	ds_read_b64_tr_b16 v[54:55], v152 offset:35328
	s_waitcnt lgkmcnt(9)
	v_mfma_f32_32x32x16_bf16 v[80:95], v[48:51], v[116:119], v[80:95]
	v_add_f32_e32 v96, v34, v97
	v_add_f32_e32 v96, v35, v96
	v_add_f32_e32 v96, v36, v96
	v_add_f32_e32 v96, v37, v96
	v_cvt_pk_bf16_f32 v100, v32, v33
	v_cvt_pk_bf16_f32 v101, v34, v35
	ds_read_b64_tr_b16 v[48:49], v152 offset:38912
	ds_read_b64_tr_b16 v[50:51], v152 offset:39424
	s_waitcnt lgkmcnt(10)
	v_mfma_f32_32x32x16_bf16 v[64:79], v[148:151], v[116:119], v[64:79]
	v_add_f32_e32 v32, v38, v96
	v_add_f32_e32 v32, v39, v32
	v_add_f32_e32 v32, v40, v32
	v_add_f32_e32 v32, v41, v32
	v_cvt_pk_bf16_f32 v102, v36, v37
	v_cvt_pk_bf16_f32 v103, v38, v39
	ds_read_b64_tr_b16 v[36:37], v152 offset:35840
	ds_read_b64_tr_b16 v[38:39], v152 offset:36352
	s_waitcnt lgkmcnt(7)
	v_mfma_f32_32x32x16_bf16 v[80:95], v[60:63], v[112:115], v[80:95]
	v_add_f32_e32 v32, v42, v32
	v_add_f32_e32 v32, v43, v32
	v_add_f32_e32 v32, v44, v32
	v_add_f32_e32 v132, v45, v32
	v_cvt_pk_bf16_f32 v96, v40, v41
	v_cvt_pk_bf16_f32 v97, v42, v43
	ds_read_b64_tr_b16 v[32:33], v152 offset:39936
	ds_read_b64_tr_b16 v[34:35], v152 offset:40448
	s_waitcnt lgkmcnt(8)
	v_mfma_f32_32x32x16_bf16 v[64:79], v[128:131], v[112:115], v[64:79]
	v_add_f32_e32 v40, v46, v132
	v_add_f32_e32 v40, v47, v40
	v_add_f32_e32 v171, 0, v40
	v_cvt_pk_bf16_f32 v98, v44, v45
	v_cvt_pk_bf16_f32 v99, v46, v47
	s_add_i32 s14, s59, 1
	s_cmp_ge_u32 s14, s53
	s_cselect_b64 s[40:41], -1, 0
	s_and_b64 vcc, exec, s[40:41]
	s_cbranch_vccnz .LBB0_620
	s_add_i32 s14, s58, 0x4000
	s_and_b32 s14, s14, 0x6000
	s_add_i32 s14, s14, s54
	s_add_u32 s15, s12, s22
	s_addc_u32 s35, s13, s23
	s_add_u32 s34, s15, 0x20000
	s_addc_u32 s35, s35, 0
	s_mov_b32 m0, s14
	s_nop 0
	global_load_lds_dwordx4 v169, s[34:35]
.LBB0_620:
	s_add_u32 s63, s20, s22
	s_addc_u32 s64, s21, s23
	s_add_u32 s34, s63, 0x10000
	s_addc_u32 s35, s64, 0
	s_add_i32 s14, s60, s55
	s_mov_b32 m0, s14
	s_nop 0
	global_load_lds_dwordx4 v170, s[34:35]
	v_mfma_f32_32x32x16_bf16 v[0:15], v[108:111], v[140:143], v[0:15]
	v_exp_f32_e32 v80, v80
	v_exp_f32_e32 v81, v81
	v_exp_f32_e32 v82, v82
	v_exp_f32_e32 v83, v83
	v_mfma_f32_32x32x16_bf16 v[16:31], v[108:111], v[144:147], v[16:31]
	v_exp_f32_e32 v84, v84
	v_exp_f32_e32 v85, v85
	v_exp_f32_e32 v86, v86
	v_exp_f32_e32 v87, v87
	v_mfma_f32_32x32x16_bf16 v[0:15], v[104:107], v[136:139], v[0:15]
	v_exp_f32_e32 v88, v88
	v_exp_f32_e32 v89, v89
	v_exp_f32_e32 v90, v90
	v_exp_f32_e32 v91, v91
	v_mfma_f32_32x32x16_bf16 v[16:31], v[104:107], v[56:59], v[16:31]
	v_exp_f32_e32 v92, v92
	v_exp_f32_e32 v93, v93
	v_exp_f32_e32 v94, v94
	v_exp_f32_e32 v95, v95
	s_and_b32 s14, s58, 0x6000
	v_add_u32_e32 v172, s14, v164
	ds_read_b128 v[44:47], v172
	ds_read_b128 v[40:43], v172 offset:512
	ds_read_b128 v[132:135], v172 offset:2048
	ds_read_b128 v[128:131], v172 offset:2560
	s_waitcnt lgkmcnt(10)
	v_mfma_f32_32x32x16_bf16 v[0:15], v[100:103], v[52:55], v[0:15]
	v_exp_f32_e32 v64, v64
	v_exp_f32_e32 v65, v65
	v_exp_f32_e32 v66, v66
	v_exp_f32_e32 v67, v67
	s_waitcnt lgkmcnt(8)
	v_mfma_f32_32x32x16_bf16 v[16:31], v[100:103], v[48:51], v[16:31]
	v_exp_f32_e32 v68, v68
	v_exp_f32_e32 v69, v69
	v_exp_f32_e32 v70, v70
	v_exp_f32_e32 v71, v71
	s_waitcnt lgkmcnt(6)
	v_mfma_f32_32x32x16_bf16 v[0:15], v[96:99], v[36:39], v[0:15]
	v_exp_f32_e32 v72, v72
	v_exp_f32_e32 v73, v73
	v_exp_f32_e32 v74, v74
	v_exp_f32_e32 v75, v75
	s_waitcnt lgkmcnt(4)
	v_mfma_f32_32x32x16_bf16 v[16:31], v[96:99], v[32:35], v[16:31]
	v_exp_f32_e32 v76, v76
	v_exp_f32_e32 v77, v77
	v_exp_f32_e32 v78, v78
	v_exp_f32_e32 v79, v79
	s_mov_b64 s[42:43], -1
	s_and_b64 vcc, exec, s[40:41]
	s_cbranch_vccz .LBB0_626
	s_add_i32 s14, s59, -2
	s_cmp_ge_u32 s14, s61
	s_cbranch_scc0 .LBB0_623
	s_waitcnt vmcnt(0) lgkmcnt(0)
	s_barrier
	s_mov_b64 s[42:43], 0

;   #define RSCALE(t) do{ if(HAS_BIAS&&((t)==tn0||(t)==tn1)){ const float f_=__builtin_amdgcn_exp2f(CREG((t)-1)-CREG(t)); l_reg*=f_; \
;     _Pragma("unroll") for(int d_=0;d_<2*VH;++d_) _Pragma("unroll") for(int r=0;r<16;++r)o[d_][r]*=f_; } }while(0)
;   #define ROT() do{sv_prev=sv_cur;sv_cur=sv_next;sv_next=(sv_next==2*VSL)?0:sv_next+VSL;}while(0)
;   #define ENDW(tt) do{ if((tt)+3<NT){WAITFULL();} else if((tt)+2<NT){ if(VH==1){WAIT_BAR(1);}else{WAIT_BAR(2);} } else {WAIT_BAR(0);} }while(0)
; template<int VH,bool HAS_BIAS,int MODE> __device__ __forceinline__ void attn_unit2(const bf16*Qb,int qp,const bf16*__restrict__ Kb,int kp,const bf16*__restrict__ Vb,int vp,bf16*Ob,int op,int q0,int NT,const float*relb,char*shm,float lam,const float*subg,float gmul){
;     ...
;     STEP(pB0,pB1,pA0,pA1,t,(t+3<NT),(t+1<NT),(t+1<NT));       ENDW(t);   RSCALE(t);   ROT();
;     STEP(pA0,pA1,pB0,pB1,t+1,(t+4<NT),(t+2<NT),(t+2<NT));     ENDW(t+1); RSCALE(t+1); ROT();
.LBB0_628:
	v_add_u32_e32 v173, s56, v167
	ds_read_b64_tr_b16 v[152:153], v173 offset:32768
	ds_read_b64_tr_b16 v[154:155], v173 offset:33280
	s_waitcnt lgkmcnt(5)
	v_mfma_f32_32x32x16_bf16 v[48:63], v[44:47], v[124:127], 0
	v_add_f32_e32 v32, v80, v81
	v_add_f32_e32 v32, v82, v32
	v_add_f32_e32 v32, v83, v32
	v_add_f32_e32 v32, v84, v32
	v_add_f32_e32 v32, v85, v32
	v_cvt_pk_bf16_f32 v108, v80, v81
	v_cvt_pk_bf16_f32 v109, v82, v83
	ds_read_b64_tr_b16 v[144:145], v173 offset:36864
	ds_read_b64_tr_b16 v[146:147], v173 offset:37376
	v_add_f32_e32 v32, v86, v32
	v_add_f32_e32 v32, v87, v32
	v_add_f32_e32 v32, v88, v32
	v_add_f32_e32 v96, v89, v32
	s_waitcnt lgkmcnt(6)
	v_mfma_f32_32x32x16_bf16 v[32:47], v[40:43], v[124:127], 0
	v_cvt_pk_bf16_f32 v110, v84, v85
	v_cvt_pk_bf16_f32 v111, v86, v87
	ds_read_b128 v[80:83], v172 offset:4096
	ds_read_b128 v[136:139], v172 offset:4608
	ds_read_b64_tr_b16 v[148:149], v173 offset:33792
	ds_read_b64_tr_b16 v[150:151], v173 offset:34304
	s_waitcnt lgkmcnt(9)
	v_mfma_f32_32x32x16_bf16 v[48:63], v[132:135], v[120:123], v[48:63]
	v_add_f32_e32 v84, v90, v96
	v_add_f32_e32 v84, v91, v84
	v_add_f32_e32 v84, v92, v84
	v_add_f32_e32 v84, v93, v84
	v_cvt_pk_bf16_f32 v104, v88, v89
	v_cvt_pk_bf16_f32 v105, v90, v91
	ds_read_b64_tr_b16 v[140:141], v173 offset:37888
	ds_read_b64_tr_b16 v[142:143], v173 offset:38400
	s_waitcnt lgkmcnt(10)
	v_mfma_f32_32x32x16_bf16 v[32:47], v[128:131], v[120:123], v[32:47]
	v_add_f32_e32 v84, v94, v84
	v_add_f32_e32 v84, v95, v84
	v_add_f32_e32 v84, v64, v84
	v_add_f32_e32 v84, v65, v84
	v_cvt_pk_bf16_f32 v106, v92, v93
	v_cvt_pk_bf16_f32 v107, v94, v95
	ds_read_b128 v[132:135], v172 offset:6144
	ds_read_b128 v[128:131], v172 offset:6656
	ds_read_b64_tr_b16 v[88:89], v173 offset:34816
	ds_read_b64_tr_b16 v[90:91], v173 offset:35328
	s_waitcnt lgkmcnt(9)
	v_mfma_f32_32x32x16_bf16 v[48:63], v[80:83], v[116:119], v[48:63]
	v_add_f32_e32 v84, v66, v84
	v_add_f32_e32 v84, v67, v84
	v_add_f32_e32 v84, v68, v84
	v_add_f32_e32 v92, v69, v84
	v_cvt_pk_bf16_f32 v100, v64, v65
	v_cvt_pk_bf16_f32 v101, v66, v67
	ds_read_b64_tr_b16 v[84:85], v173 offset:38912
	ds_read_b64_tr_b16 v[86:87], v173 offset:39424
	s_waitcnt lgkmcnt(10)
	v_mfma_f32_32x32x16_bf16 v[32:47], v[136:139], v[116:119], v[32:47]
	v_add_f32_e32 v64, v70, v92
	v_add_f32_e32 v64, v71, v64
	v_add_f32_e32 v64, v72, v64
	v_add_f32_e32 v64, v73, v64
	v_cvt_pk_bf16_f32 v102, v68, v69
	v_cvt_pk_bf16_f32 v103, v70, v71
	ds_read_b64_tr_b16 v[68:69], v173 offset:35840
	ds_read_b64_tr_b16 v[70:71], v173 offset:36352
	s_waitcnt lgkmcnt(7)
	v_mfma_f32_32x32x16_bf16 v[48:63], v[132:135], v[112:115], v[48:63]
	v_add_f32_e32 v64, v74, v64
	v_add_f32_e32 v64, v75, v64
	v_add_f32_e32 v64, v76, v64
	v_add_f32_e32 v92, v77, v64
	v_cvt_pk_bf16_f32 v96, v72, v73
	v_cvt_pk_bf16_f32 v97, v74, v75
	ds_read_b64_tr_b16 v[64:65], v173 offset:39936
	ds_read_b64_tr_b16 v[66:67], v173 offset:40448
	s_waitcnt lgkmcnt(8)
	v_mfma_f32_32x32x16_bf16 v[32:47], v[128:131], v[112:115], v[32:47]
	v_add_f32_e32 v72, v78, v92
	v_add_f32_e32 v72, v79, v72
	v_add_f32_e32 v72, 0, v72
	v_cvt_pk_bf16_f32 v98, v76, v77
	v_cvt_pk_bf16_f32 v99, v78, v79
	s_add_i32 s65, s59, 2
	s_cmp_ge_u32 s65, s53
	s_cselect_b64 s[42:43], -1, 0
	s_and_b64 vcc, exec, s[42:43]
	s_cbranch_vccnz .LBB0_630
	s_add_i32 s14, s62, s54
	s_add_u32 s15, s12, s22
	s_addc_u32 s35, s13, s23
	s_add_u32 s34, s15, 0x28000
	s_addc_u32 s35, s35, 0
	s_mov_b32 m0, s14
	s_nop 0
	global_load_lds_dwordx4 v169, s[34:35]
.LBB0_630:
	s_add_i32 s14, s60, 0x2000
	s_cmpk_lg_i32 s60, 0x4000
	s_cselect_b32 s56, s14, 0
	s_cmp_lt_u32 s59, s53
	s_cselect_b64 s[44:45], -1, 0
	s_cmp_ge_u32 s59, s53
	s_cbranch_scc1 .LBB0_632
	s_add_i32 s14, s56, s55
	s_add_u32 s34, s63, 0x18000
	s_addc_u32 s35, s64, 0
	s_mov_b32 m0, s14
	s_nop 0
	global_load_lds_dwordx4 v170, s[34:35]

; #define WAIT_BAR(N) asm volatile("s_waitcnt vmcnt(" #N ") lgkmcnt(0)\n\ts_barrier":::"memory")
;   #define DMA_K(t,slot) glds16s(Kb+(long)(t)*KVBLK*kp,ksrc,(unsigned)__builtin_amdgcn_readfirstlane(kdst+(slot)))
;   #define DMA_V(t,slot) do{ glds16s(Vb+(long)(t)*KVBLK*vp,vsrc,(unsigned)__builtin_amdgcn_readfirstlane(vdst+(slot))); \
;       if(VH==2) glds16s(Vb+(long)(t)*KVBLK*vp+64,vsrc,(unsigned)__builtin_amdgcn_readfirstlane(vdst+(slot)+8192)); }while(0)
;   #define BIASADD(P0,P1,t) do{ if(HAS_BIAS&&(t)>=tn0&&(t)<tn1){ const lds_f32*bp_=btab+(64*(t)+lanebias); \
;     _Pragma("unroll") for(int r=0;r<16;++r){ P0[r]+=bp_[(r&3)+8*(r>>2)]; P1[r]+=bp_[(r&3)+8*(r>>2)+32]; } } }while(0)
; template<int VH,bool HAS_BIAS,int MODE> __device__ __forceinline__ void attn_unit2(const bf16*Qb,int qp,const bf16*__restrict__ Kb,int kp,const bf16*__restrict__ Vb,int vp,bf16*Ob,int op,int q0,int NT,const float*relb,char*shm,float lam,const float*subg,float gmul){
;     ...
;   const int qw_=q0+32*wid; const int tn0=HAS_BIAS?(qw_>=90?((qw_-90)>>6):0):0, tn1=HAS_BIAS?(((qw_+185)>>6)<NT?((qw_+185)>>6):NT):0;
;   float cb=0.f,ca=0.f;
;   typedef __attribute__((address_space(3))) float lds_f32;
;   typedef __attribute__((address_space(3))) char* lds_ptr_;
;   lds_f32* btab=(lds_f32*)((lds_ptr_)shm)+LM::L_BT/4;
;   if(HAS_BIAS){ const float L2E=1.4426950408889634f; cb=L2E*relb[15*8]; ca=L2E*relb[31*8];
;     for(int i=tid;i<768;i+=512){ const int rel=i-384; const int n=rel<0?-rel:rel; int bk=n<8?n:(8+(31-__builtin_clz((unsigned)(n*n)))-6); if(n>=8&&bk>15)bk=15; if(rel>0)bk+=16; btab[i]=L2E*relb[bk*8]; } }
;   const int lanebias=-q0-32*wid-r32+4*hi+384;
;     ...
;   DMA_K(0,0);DMA_V(0,0);DMA_K(1,KSL);
;   bf16x8 qr[4];
;   #pragma unroll
;   for(int d0=0;d0<4;++d0)qr[d0]=*reinterpret_cast<const bf16x8*>(&Qw[(long)r32*qp+d0*16+hi*8]);
;   DMA_K(2,2*KSL);
;   float l_reg=0.f;f32x16 o[2*VH];
;   #pragma unroll
;   for(int d_=0;d_<2*VH;++d_)o[d_]=f32x16{};
;   const f32x16 zero16=f32x16{};
;   f32x16 pA0,pA1,pB0,pB1; bf16x8 kf[4];
;   int sv_prev=0,sv_cur=0,sv_next=VSL;
;     ...
;   if(VH==1){WAIT_BAR(3);}else{WAIT_BAR(4);}
;   qkt(pA0,pA1,shm+LM::L_K,qr,zero16,r32,hi);
;   BIASADD(pA0,pA1,0);
.LBB0_1085:
	s_or_b64 exec, exec, s[42:43]
	s_lshl_b64 s[22:23], s[22:23], 1
	s_add_u32 s6, s28, s22
	s_addc_u32 s7, s29, s23
	s_lshl_b32 s68, s16, 7
	s_lshl_b32 s8, s16, 8
	s_add_u32 s75, s6, s8
	s_addc_u32 s76, s7, 0
	s_add_u32 s6, s36, s22
	s_addc_u32 s7, s37, s23
	s_add_u32 s44, s6, s8
	s_addc_u32 s45, s7, 0
	s_add_u32 s6, s38, s22
	s_addc_u32 s7, s39, s23
	s_add_u32 s46, s6, s8
	s_addc_u32 s47, s7, 0
	s_ashr_i32 s8, s56, 6
	s_lshl_b32 s77, s54, 8
	s_lshl_b32 s6, s8, 5
	s_add_i32 s6, s6, s77
	s_ashr_i32 s7, s6, 31
	s_lshl_b64 s[10:11], s[6:7], 11
	s_add_u32 s10, s75, s10
	v_and_b32_e32 v193, 63, v184
	s_addc_u32 s11, s76, s11
	s_lshl_b32 s7, s8, 4
	v_bfe_u32 v2, v184, 2, 4
	v_lshl_add_u32 v202, v193, 11, s7
	v_and_or_b32 v2, s7, 48, v2
	s_ashr_i32 s7, s56, 3
	s_and_b32 s7, s7, 0x7fffffe0
	v_lshl_add_u32 v2, v2, 10, s7
	s_lshl_b32 s7, s8, 10
	s_cmp_lg_u32 0, -1
	s_cselect_b32 s9, 0, 0
	s_add_i32 s33, s7, s9
	s_add_i32 s9, s6, 0xffffffa6
	s_add_i32 s59, s33, 0x8000
	s_ashr_i32 s9, s9, 6
	v_lshlrev_b32_e32 v3, 3, v184
	s_cmpk_gt_i32 s6, 0x59
	v_and_b32_e32 v195, 24, v3
	s_cselect_b32 s57, s9, 0
	s_add_i32 s9, s6, 0xb9
	v_or_b32_e32 v2, v2, v195
	s_ashr_i32 s58, s9, 6
	s_mov_b32 m0, s33
	s_nop 0
	global_load_lds_dwordx4 v202, s[44:45]
	v_lshlrev_b32_e32 v203, 1, v2
	s_mov_b32 m0, s59
	s_nop 0
	global_load_lds_dwordx4 v203, s[46:47]
	s_add_u32 s48, s46, 0x80
	v_and_b32_e32 v185, 31, v184
	s_addc_u32 s49, s47, 0
	s_add_i32 s9, s33, 0xa000
	v_bfe_u32 v35, v184, 5, 1
	s_mov_b32 m0, s9
	s_nop 0
	global_load_lds_dwordx4 v203, s[48:49]
	s_add_u32 s42, s44, 0x20000
	v_lshlrev_b32_e32 v2, 11, v185
	s_addc_u32 s43, s45, 0
	s_add_i32 s9, s33, 0x2000
	s_mov_b32 m0, s9
	s_nop 0
	global_load_lds_dwordx4 v202, s[42:43]
	v_lshl_or_b32 v2, v35, 4, v2
	global_load_dwordx4 v[158:161], v2, s[10:11]
	global_load_dwordx4 v[154:157], v2, s[10:11] offset:32
	global_load_dwordx4 v[150:153], v2, s[10:11] offset:64
	global_load_dwordx4 v[146:149], v2, s[10:11] offset:96
	s_add_u32 s10, s44, 0x40000
	v_lshlrev_b32_e32 v2, 10, v35
	v_lshlrev_b32_e32 v3, 4, v185
	s_addc_u32 s11, s45, 0
	s_add_i32 s9, s33, 0x4000
	s_mov_b32 m0, s9
	s_nop 0
	global_load_lds_dwordx4 v202, s[10:11]
	v_add3_u32 v201, 0, v2, v3
	s_waitcnt vmcnt(4) lgkmcnt(0)
	s_barrier
	ds_read_b128 v[2:5], v201
	ds_read_b128 v[18:21], v201 offset:512
	ds_read_b128 v[36:39], v201 offset:2048
	s_cmp_lt_i32 s57, 1
	s_cselect_b64 s[10:11], -1, 0
	s_cmp_gt_i32 s58, 0
	s_cselect_b64 s[42:43], -1, 0
	s_and_b64 s[10:11], s[10:11], s[42:43]
	v_lshlrev_b32_e32 v194, 2, v35
	v_or_b32_e32 v200, s6, v185
	s_and_b64 vcc, exec, s[10:11]
	s_waitcnt vmcnt(3) lgkmcnt(2)
	v_mfma_f32_32x32x16_bf16 v[2:17], v[2:5], v[158:161], 0
	s_waitcnt vmcnt(2) lgkmcnt(0)
	v_mfma_f32_32x32x16_bf16 v[2:17], v[36:39], v[154:157], v[2:17]
	ds_read_b128 v[36:39], v201 offset:2560
	v_mfma_f32_32x32x16_bf16 v[18:33], v[18:21], v[158:161], 0
	s_waitcnt lgkmcnt(0)
	v_mfma_f32_32x32x16_bf16 v[18:33], v[36:39], v[154:157], v[18:33]
	ds_read_b128 v[36:39], v201 offset:4096
	s_waitcnt vmcnt(1) lgkmcnt(0)
	v_mfma_f32_32x32x16_bf16 v[2:17], v[36:39], v[150:153], v[2:17]
	ds_read_b128 v[36:39], v201 offset:4608
	s_waitcnt lgkmcnt(0)
	v_mfma_f32_32x32x16_bf16 v[18:33], v[36:39], v[150:153], v[18:33]
	ds_read_b128 v[36:39], v201 offset:6144
	s_waitcnt vmcnt(0) lgkmcnt(0)
	v_mfma_f32_32x32x16_bf16 v[2:17], v[36:39], v[146:149], v[2:17]
	ds_read_b128 v[36:39], v201 offset:6656
	s_waitcnt lgkmcnt(0)
	v_mfma_f32_32x32x16_bf16 v[18:33], v[36:39], v[146:149], v[18:33]
	s_cbranch_vccz .LBB0_1087
	v_or_b32_e32 v36, 0x180, v194
	v_sub_u32_e32 v36, v36, v200
	v_lshl_add_u32 v36, v36, 2, 0
	v_add_u32_e32 v60, 0x14800, v36
	ds_read2_b32 v[36:37], v60 offset1:1
	ds_read2_b32 v[38:39], v60 offset0:2 offset1:3
	ds_read2_b32 v[40:41], v60 offset0:8 offset1:9
	ds_read2_b32 v[42:43], v60 offset0:10 offset1:11
	ds_read2_b32 v[44:45], v60 offset0:16 offset1:17
	ds_read2_b32 v[46:47], v60 offset0:18 offset1:19
	ds_read2_b32 v[48:49], v60 offset0:24 offset1:25
	ds_read2_b32 v[50:51], v60 offset0:26 offset1:27
	ds_read2_b32 v[52:53], v60 offset0:32 offset1:33
	ds_read2_b32 v[54:55], v60 offset0:34 offset1:35
	ds_read2_b32 v[56:57], v60 offset0:40 offset1:41
	ds_read2_b32 v[58:59], v60 offset0:42 offset1:43
	s_waitcnt lgkmcnt(4)
	v_pk_add_f32 v[16:17], v[16:17], v[50:51]
	v_pk_add_f32 v[14:15], v[14:15], v[48:49]
	v_pk_add_f32 v[12:13], v[12:13], v[46:47]
	v_pk_add_f32 v[10:11], v[10:11], v[44:45]
	ds_read2_b32 v[44:45], v60 offset0:48 offset1:49
	ds_read2_b32 v[46:47], v60 offset0:50 offset1:51
	ds_read2_b32 v[48:49], v60 offset0:56 offset1:57
	ds_read2_b32 v[50:51], v60 offset0:58 offset1:59
	v_pk_add_f32 v[8:9], v[8:9], v[42:43]
	v_pk_add_f32 v[6:7], v[6:7], v[40:41]
	v_pk_add_f32 v[4:5], v[4:5], v[38:39]
	v_pk_add_f32 v[2:3], v[2:3], v[36:37]
	s_waitcnt lgkmcnt(0)
	v_pk_add_f32 v[32:33], v[32:33], v[50:51]
	v_pk_add_f32 v[30:31], v[30:31], v[48:49]
	v_pk_add_f32 v[28:29], v[28:29], v[46:47]
	v_pk_add_f32 v[26:27], v[26:27], v[44:45]
	v_pk_add_f32 v[24:25], v[24:25], v[58:59]
	v_pk_add_f32 v[22:23], v[22:23], v[56:57]
	v_pk_add_f32 v[20:21], v[20:21], v[54:55]
	v_pk_add_f32 v[18:19], v[18:19], v[52:53]
; #define WAIT_BAR(N) asm volatile("s_waitcnt vmcnt(" #N ") lgkmcnt(0)\n\ts_barrier":::"memory")
;   #define DMA_K(t,slot) glds16s(Kb+(long)(t)*KVBLK*kp,ksrc,(unsigned)__builtin_amdgcn_readfirstlane(kdst+(slot)))
;   #define DMA_V(t,slot) do{ glds16s(Vb+(long)(t)*KVBLK*vp,vsrc,(unsigned)__builtin_amdgcn_readfirstlane(vdst+(slot))); \
;       if(VH==2) glds16s(Vb+(long)(t)*KVBLK*vp+64,vsrc,(unsigned)__builtin_amdgcn_readfirstlane(vdst+(slot)+8192)); }while(0)
;   #define BIASADD(P0,P1,t) do{ if(HAS_BIAS&&(t)>=tn0&&(t)<tn1){ const lds_f32*bp_=btab+(64*(t)+lanebias); \
;     _Pragma("unroll") for(int r=0;r<16;++r){ P0[r]+=bp_[(r&3)+8*(r>>2)]; P1[r]+=bp_[(r&3)+8*(r>>2)+32]; } } }while(0)
;   #define ROT() do{sv_prev=sv_cur;sv_cur=sv_next;sv_next=(sv_next==2*VSL)?0:sv_next+VSL;}while(0)
;   #define KPRE(tn) do{ const lds_cptr kn_=kp0+(((tn)&3)*KSL); kf[0]=KLD(kn_); kf[1]=KLD(kn_+512); kf[2]=KLD(kn_+2048); kf[3]=KLD(kn_+2560); }while(0)
; template<int VH,bool HAS_BIAS,int MODE> __device__ __forceinline__ void attn_unit2(const bf16*Qb,int qp,const bf16*__restrict__ Kb,int kp,const bf16*__restrict__ Vb,int vp,bf16*Ob,int op,int q0,int NT,const float*relb,char*shm,float lam,const float*subg,float gmul){
;     ...
;   float l_reg=0.f;f32x16 o[2*VH];
;   #pragma unroll
;   for(int d_=0;d_<2*VH;++d_)o[d_]=f32x16{};
;   const f32x16 zero16=f32x16{};
;   f32x16 pA0,pA1,pB0,pB1; bf16x8 kf[4];
;   int sv_prev=0,sv_cur=0,sv_next=VSL;
;     ...
;   if(VH==1){WAIT_BAR(3);}else{WAIT_BAR(4);}
;   qkt(pA0,pA1,shm+LM::L_K,qr,zero16,r32,hi);
;   BIASADD(pA0,pA1,0);
;   _Pragma("unroll") for(int r=0;r<16;++r){pA0[r]=__builtin_amdgcn_exp2f(pA0[r]);pA1[r]=__builtin_amdgcn_exp2f(pA1[r]);}
;   WAIT_BAR(0);
;   DMA_K(3,3*KSL);DMA_V(1,VSL);
;   ROT();
;   KPRE(1);
;   s16x4 vlo[8],vhi[8]; u32x4 pw0,pw1,pw2,pw3;
.LBB0_1087:
	s_min_i32 s60, s58, s69
	s_add_u32 s42, s44, 0x60000
	s_addc_u32 s43, s45, 0
	s_cmp_lg_u32 0, -1
	s_cselect_b32 s9, 0, 0
	s_add_i32 s7, s9, s7
	s_add_i32 s9, s7, 0x6000
	s_waitcnt vmcnt(0) lgkmcnt(0)
	s_barrier
	s_add_u32 s50, s46, 0x20000
	s_mov_b32 m0, s9
	s_nop 0
	global_load_lds_dwordx4 v202, s[42:43]
	s_addc_u32 s51, s47, 0
	s_add_i32 s9, s7, 0xc000
	s_mov_b32 m0, s9
	s_nop 0
	global_load_lds_dwordx4 v203, s[50:51]
	s_add_u32 s52, s46, 0x20080
	v_mul_f32_e32 v198, 0x3fb8aa3b, v0
	s_addc_u32 s53, s47, 0
	s_add_i32 s7, s7, 0xe000
	s_mov_b32 m0, s7
	s_nop 0
	global_load_lds_dwordx4 v203, s[52:53]
	v_exp_f32_e32 v82, v2
	v_lshlrev_b32_e32 v0, 4, v35
	v_lshlrev_b32_e32 v2, 2, v185
	s_add_i32 s70, s69, -5
	v_sub_u32_e32 v0, v0, v2
	s_lshl_b32 s7, s8, 7
	s_lshl_b32 s78, s54, 10
	s_add_i32 s79, 0, 0x14f00
	s_lshl_b64 s[8:9], s[16:17], 8
	v_lshlrev_b32_e32 v36, 1, v184
	ds_read_b128 v[162:165], v201 offset:10752
	ds_read_b128 v[166:169], v201 offset:10240
	ds_read_b128 v[170:173], v201 offset:8704
	ds_read_b128 v[114:117], v201 offset:8192
	v_subrev_u32_e32 v0, s7, v0
	s_add_u32 s7, s8, s22
	v_and_b32_e32 v197, 32, v36
	v_lshrrev_b32_e32 v36, 2, v184
	s_addc_u32 s8, s9, s23
	v_and_or_b32 v36, v36, 3, v194
	s_add_u32 s71, s30, s7
	v_lshlrev_b32_e32 v196, 6, v36
	v_add_u32_e32 v36, 0, v197
	v_exp_f32_e32 v66, v18
	v_exp_f32_e32 v67, v19
	v_exp_f32_e32 v68, v20
	v_exp_f32_e32 v69, v21
	v_exp_f32_e32 v70, v22
	v_exp_f32_e32 v71, v23
	v_exp_f32_e32 v72, v24
	v_exp_f32_e32 v73, v25
	v_exp_f32_e32 v74, v26
	v_exp_f32_e32 v75, v27
	v_exp_f32_e32 v76, v28
	v_exp_f32_e32 v77, v29
	v_exp_f32_e32 v78, v30
	v_exp_f32_e32 v79, v31
	v_exp_f32_e32 v80, v32
	v_exp_f32_e32 v81, v33
	v_exp_f32_e32 v83, v3
	v_exp_f32_e32 v84, v4
	v_exp_f32_e32 v85, v5
	v_exp_f32_e32 v86, v6
	v_exp_f32_e32 v87, v7
	v_exp_f32_e32 v88, v8
	v_exp_f32_e32 v89, v9
	v_exp_f32_e32 v90, v10
	v_exp_f32_e32 v91, v11
	v_exp_f32_e32 v92, v12
	v_exp_f32_e32 v93, v13
	v_exp_f32_e32 v94, v14
	v_exp_f32_e32 v95, v15
	v_exp_f32_e32 v96, v16
	v_exp_f32_e32 v97, v17
	v_subrev_u32_e32 v0, s78, v0
	s_addc_u32 s73, s31, s8
	s_add_i32 s80, 0, 0x15100
	v_mov_b32_e32 v14, v1
	v_mov_b32_e32 v15, v1
	v_add3_u32 v204, v36, v195, v196
	v_mul_f32_e32 v199, 0x3fb8aa3b, v34
	v_add_u32_e32 v179, s79, v0
	v_add_u32_e32 v205, s80, v0
	v_mov_b32_e32 v0, v1
	v_mov_b32_e32 v2, v1
	v_mov_b32_e32 v3, v1
	v_mov_b32_e32 v4, v1
	v_mov_b32_e32 v5, v1
	v_mov_b32_e32 v6, v1
	v_mov_b32_e32 v7, v1
	v_mov_b32_e32 v8, v1
	v_mov_b32_e32 v9, v1
	v_mov_b32_e32 v10, v1
	v_mov_b32_e32 v11, v1
	v_mov_b32_e32 v12, v1
	v_mov_b32_e32 v13, v1
	v_mov_b64_e32 v[64:65], v[14:15]
	v_mov_b64_e32 v[48:49], v[14:15]
	v_mov_b64_e32 v[32:33], v[14:15]
	v_mov_b64_e32 v[62:63], v[12:13]
	v_mov_b64_e32 v[60:61], v[10:11]
	v_mov_b64_e32 v[58:59], v[8:9]
	v_mov_b64_e32 v[56:57], v[6:7]
	v_mov_b64_e32 v[54:55], v[4:5]
	v_mov_b64_e32 v[52:53], v[2:3]
	v_mov_b64_e32 v[50:51], v[0:1]
	v_mov_b64_e32 v[46:47], v[12:13]
	v_mov_b64_e32 v[44:45], v[10:11]
	v_mov_b64_e32 v[42:43], v[8:9]
	v_mov_b64_e32 v[40:41], v[6:7]
	v_mov_b64_e32 v[38:39], v[4:5]
	v_mov_b64_e32 v[36:37], v[2:3]
	v_mov_b64_e32 v[34:35], v[0:1]
	v_mov_b64_e32 v[30:31], v[12:13]
	v_mov_b64_e32 v[28:29], v[10:11]
	v_mov_b64_e32 v[26:27], v[8:9]
	v_mov_b64_e32 v[24:25], v[6:7]
	v_mov_b64_e32 v[22:23], v[4:5]
	v_mov_b64_e32 v[20:21], v[2:3]
	v_mov_b64_e32 v[18:19], v[0:1]
	v_mov_b64_e32 v[16:17], v[14:15]
	s_mov_b32 s10, 1
	s_mov_b32 s61, 2
	s_mov_b32 s6, 0
	s_mov_b32 s84, 4
	s_sub_i32 s74, 0, s60
	s_sub_i32 s81, 0, s57
	v_mov_b32_e32 v178, 0
	s_movk_i32 s42, 0x4000
	s_mov_b64 s[8:9], 0
	s_mov_b32 s82, 0x8000
	v_mov_b64_e32 v[14:15], v[12:13]
	v_mov_b64_e32 v[12:13], v[10:11]
	v_mov_b64_e32 v[10:11], v[8:9]
	v_mov_b64_e32 v[8:9], v[6:7]
	v_mov_b64_e32 v[6:7], v[4:5]
	v_mov_b64_e32 v[4:5], v[2:3]
	v_mov_b64_e32 v[2:3], v[0:1]
	s_movk_i32 s55, 0x4000
	s_mov_b32 s11, 0x8000
.LBB0_1088:
	v_add_u32_e32 v0, s6, v204
	ds_read_b64_tr_b16 v[174:175], v0 offset:32768
	ds_read_b64_tr_b16 v[176:177], v0 offset:33280
	s_add_i32 s6, s42, 0xffffe000
	s_and_b32 s54, s6, 0x6000
	v_add_u32_e32 v130, s54, v201
	s_waitcnt lgkmcnt(2)
	v_mfma_f32_32x32x16_bf16 v[114:129], v[114:117], v[158:161], 0
	v_add_f32_e32 v98, v82, v83
	v_add_f32_e32 v98, v84, v98
	v_add_f32_e32 v98, v85, v98
	v_add_f32_e32 v98, v86, v98
	v_add_f32_e32 v98, v87, v98
	v_cvt_pk_bf16_f32 v142, v82, v83
	v_cvt_pk_bf16_f32 v143, v84, v85
	ds_read_b64_tr_b16 v[82:83], v0 offset:36864
	ds_read_b64_tr_b16 v[84:85], v0 offset:37376
	v_add_f32_e32 v98, v88, v98
	v_add_f32_e32 v98, v89, v98
	v_add_f32_e32 v98, v90, v98
	v_add_f32_e32 v131, v91, v98
	v_mfma_f32_32x32x16_bf16 v[98:113], v[170:173], v[158:161], 0
	v_cvt_pk_bf16_f32 v144, v86, v87
	v_cvt_pk_bf16_f32 v145, v88, v89
	ds_read_b128 v[170:173], v130 offset:4096
	ds_read_b128 v[206:209], v130 offset:4608
	ds_read_b64_tr_b16 v[86:87], v0 offset:33792
	ds_read_b64_tr_b16 v[88:89], v0 offset:34304
	v_mfma_f32_32x32x16_bf16 v[114:129], v[166:169], v[154:157], v[114:129]
	v_add_f32_e32 v131, v92, v131
	v_add_f32_e32 v131, v93, v131
	v_add_f32_e32 v131, v94, v131
	v_add_f32_e32 v131, v95, v131
	v_cvt_pk_bf16_f32 v138, v90, v91
	v_cvt_pk_bf16_f32 v139, v92, v93
	ds_read_b64_tr_b16 v[90:91], v0 offset:37888
	ds_read_b64_tr_b16 v[92:93], v0 offset:38400
	v_mfma_f32_32x32x16_bf16 v[98:113], v[162:165], v[154:157], v[98:113]
	v_add_f32_e32 v131, v96, v131
	v_add_f32_e32 v131, v97, v131
	v_add_f32_e32 v131, v66, v131
	v_add_f32_e32 v131, v67, v131
	v_cvt_pk_bf16_f32 v140, v94, v95
	v_cvt_pk_bf16_f32 v141, v96, v97
	ds_read_b128 v[162:165], v130 offset:6144
	ds_read_b128 v[166:169], v130 offset:6656
	ds_read_b64_tr_b16 v[94:95], v0 offset:34816
	ds_read_b64_tr_b16 v[96:97], v0 offset:35328
	s_waitcnt lgkmcnt(9)
	v_mfma_f32_32x32x16_bf16 v[114:129], v[170:173], v[150:153], v[114:129]
	v_add_f32_e32 v130, v68, v131
	v_add_f32_e32 v130, v69, v130
	v_add_f32_e32 v130, v70, v130
	v_add_f32_e32 v130, v71, v130
	v_cvt_pk_bf16_f32 v134, v66, v67
	v_cvt_pk_bf16_f32 v135, v68, v69
	ds_read_b64_tr_b16 v[66:67], v0 offset:38912
	ds_read_b64_tr_b16 v[68:69], v0 offset:39424
	s_waitcnt lgkmcnt(10)
	v_mfma_f32_32x32x16_bf16 v[98:113], v[206:209], v[150:153], v[98:113]
	v_add_f32_e32 v130, v72, v130
	v_add_f32_e32 v130, v73, v130
	v_add_f32_e32 v130, v74, v130
	v_add_f32_e32 v130, v75, v130
	v_cvt_pk_bf16_f32 v136, v70, v71
	v_cvt_pk_bf16_f32 v137, v72, v73
	ds_read_b64_tr_b16 v[70:71], v0 offset:35840
	ds_read_b64_tr_b16 v[72:73], v0 offset:36352
	s_waitcnt lgkmcnt(7)
	v_mfma_f32_32x32x16_bf16 v[114:129], v[162:165], v[146:149], v[114:129]
	v_add_f32_e32 v130, v76, v130
	v_add_f32_e32 v130, v77, v130
	v_add_f32_e32 v130, v78, v130
	v_add_f32_e32 v170, v79, v130
	v_cvt_pk_bf16_f32 v130, v74, v75
	v_cvt_pk_bf16_f32 v131, v76, v77
	ds_read_b64_tr_b16 v[74:75], v0 offset:39936
	ds_read_b64_tr_b16 v[76:77], v0 offset:40448
	s_waitcnt lgkmcnt(8)
	v_mfma_f32_32x32x16_bf16 v[98:113], v[166:169], v[146:149], v[98:113]
	v_add_f32_e32 v132, v80, v170
	v_add_f32_e32 v132, v81, v132
	v_add_f32_e32 v162, 0, v132
	v_cvt_pk_bf16_f32 v132, v78, v79
	v_cvt_pk_bf16_f32 v133, v80, v81
	s_add_u32 s87, s44, s8
	s_addc_u32 s88, s45, s9
	s_add_u32 s6, s87, 0x80000
	s_addc_u32 s7, s88, 0
	s_add_i32 s16, s42, 0x4000
	s_and_b32 s12, s16, 0x6000
	s_add_i32 s12, s12, s33
	s_add_u32 s85, s71, s8
	s_addc_u32 s86, s73, s9
	s_mov_b32 m0, s12
	s_nop 0
	global_load_lds_dwordx4 v202, s[6:7]
	s_add_u32 s6, s85, 0x22040000
	s_addc_u32 s7, s86, 0
	s_add_i32 s12, s11, s59
	s_add_u32 s90, s85, 0x22040080
	s_mov_b32 m0, s12
	s_nop 0
	global_load_lds_dwordx4 v203, s[6:7]
	s_addc_u32 s91, s86, 0
	s_addk_i32 s12, 0x2000
	s_cmp_ge_i32 s10, s57
	s_cselect_b64 s[92:93], -1, 0
	s_cmp_gt_i32 s58, s10
	s_cselect_b64 s[6:7], -1, 0
	s_mov_b32 m0, s12
	s_nop 0
	global_load_lds_dwordx4 v203, s[90:91]
	s_and_b64 s[92:93], s[92:93], s[6:7]
	s_andn2_b64 vcc, exec, s[92:93]
	s_cbranch_vccnz .LBB0_1090
	ds_read2_b32 v[78:79], v179 offset1:1
	ds_read2_b32 v[80:81], v179 offset0:2 offset1:3
	ds_read2_b32 v[164:165], v179 offset0:8 offset1:9
	ds_read2_b32 v[166:167], v179 offset0:10 offset1:11
	ds_read2_b32 v[168:169], v179 offset0:16 offset1:17
	ds_read2_b32 v[170:171], v179 offset0:18 offset1:19
	ds_read2_b32 v[172:173], v179 offset0:24 offset1:25
	ds_read2_b32 v[180:181], v179 offset0:26 offset1:27
	ds_read2_b32 v[206:207], v179 offset0:32 offset1:33
	ds_read2_b32 v[208:209], v179 offset0:34 offset1:35
	ds_read2_b32 v[210:211], v179 offset0:40 offset1:41
	ds_read2_b32 v[212:213], v179 offset0:42 offset1:43
	s_waitcnt lgkmcnt(11)
	v_pk_add_f32 v[114:115], v[114:115], v[78:79]
	s_waitcnt lgkmcnt(5)
	v_pk_add_f32 v[126:127], v[126:127], v[172:173]
	v_pk_add_f32 v[124:125], v[124:125], v[170:171]
	v_pk_add_f32 v[122:123], v[122:123], v[168:169]
	ds_read2_b32 v[78:79], v179 offset0:48 offset1:49
	ds_read2_b32 v[168:169], v179 offset0:50 offset1:51
	ds_read2_b32 v[170:171], v179 offset0:56 offset1:57
	ds_read2_b32 v[172:173], v179 offset0:58 offset1:59
	s_waitcnt lgkmcnt(8)
	v_pk_add_f32 v[128:129], v[128:129], v[180:181]
	v_pk_add_f32 v[120:121], v[120:121], v[166:167]
	v_pk_add_f32 v[118:119], v[118:119], v[164:165]
	v_pk_add_f32 v[116:117], v[116:117], v[80:81]
	s_waitcnt lgkmcnt(7)
	v_pk_add_f32 v[98:99], v[98:99], v[206:207]
	s_waitcnt lgkmcnt(0)
	v_pk_add_f32 v[112:113], v[112:113], v[172:173]
	v_pk_add_f32 v[110:111], v[110:111], v[170:171]
	v_pk_add_f32 v[108:109], v[108:109], v[168:169]
	v_pk_add_f32 v[106:107], v[106:107], v[78:79]
	v_pk_add_f32 v[104:105], v[104:105], v[212:213]
	v_pk_add_f32 v[102:103], v[102:103], v[210:211]
	v_pk_add_f32 v[100:101], v[100:101], v[208:209]

.LBB0_1092:
	s_add_i32 s89, s10, 1
	s_add_i32 s6, s11, 0x4000
	s_cmpk_lg_u32 s11, 0x8000
	s_cselect_b32 s83, s6, 0
	v_add_u32_e32 v174, s55, v204
	ds_read_b64_tr_b16 v[170:171], v174 offset:32768
	ds_read_b64_tr_b16 v[172:173], v174 offset:33280
	s_waitcnt lgkmcnt(5)
	v_mfma_f32_32x32x16_bf16 v[82:97], v[70:73], v[158:161], 0
	v_add_f32_e32 v74, v114, v115
	v_add_f32_e32 v74, v116, v74
	v_add_f32_e32 v74, v117, v74
	v_add_f32_e32 v74, v118, v74
	v_add_f32_e32 v74, v119, v74
	v_cvt_pk_bf16_f32 v142, v114, v115
	v_cvt_pk_bf16_f32 v143, v116, v117
	ds_read_b64_tr_b16 v[114:115], v174 offset:36864
	ds_read_b64_tr_b16 v[116:117], v174 offset:37376
	v_add_f32_e32 v70, v120, v74
	v_add_f32_e32 v70, v121, v70
	v_add_f32_e32 v70, v122, v70
	v_add_f32_e32 v130, v123, v70
	s_waitcnt lgkmcnt(6)
	v_mfma_f32_32x32x16_bf16 v[66:81], v[66:69], v[158:161], 0
	v_cvt_pk_bf16_f32 v144, v118, v119
	v_cvt_pk_bf16_f32 v145, v120, v121
	ds_read_b128 v[206:209], v175 offset:4096
	ds_read_b128 v[210:213], v175 offset:4608
	ds_read_b64_tr_b16 v[118:119], v174 offset:33792
	ds_read_b64_tr_b16 v[120:121], v174 offset:34304
	s_waitcnt lgkmcnt(9)
	v_mfma_f32_32x32x16_bf16 v[82:97], v[166:169], v[154:157], v[82:97]
	v_add_f32_e32 v130, v124, v130
	v_add_f32_e32 v130, v125, v130
	v_add_f32_e32 v130, v126, v130
	v_add_f32_e32 v130, v127, v130
	v_cvt_pk_bf16_f32 v138, v122, v123
	v_cvt_pk_bf16_f32 v139, v124, v125
	ds_read_b64_tr_b16 v[122:123], v174 offset:37888
	ds_read_b64_tr_b16 v[124:125], v174 offset:38400
	s_waitcnt lgkmcnt(10)
	v_mfma_f32_32x32x16_bf16 v[66:81], v[162:165], v[154:157], v[66:81]
	v_add_f32_e32 v130, v128, v130
	v_add_f32_e32 v130, v129, v130
	v_add_f32_e32 v130, v98, v130
	v_add_f32_e32 v130, v99, v130
	v_cvt_pk_bf16_f32 v140, v126, v127
	v_cvt_pk_bf16_f32 v141, v128, v129
	ds_read_b128 v[162:165], v175 offset:6144
	ds_read_b128 v[166:169], v175 offset:6656
	ds_read_b64_tr_b16 v[126:127], v174 offset:34816
	ds_read_b64_tr_b16 v[128:129], v174 offset:35328
	s_waitcnt lgkmcnt(9)
	v_mfma_f32_32x32x16_bf16 v[82:97], v[206:209], v[150:153], v[82:97]
	v_add_f32_e32 v130, v100, v130
	v_add_f32_e32 v130, v101, v130
	v_add_f32_e32 v130, v102, v130
	v_add_f32_e32 v130, v103, v130
	v_cvt_pk_bf16_f32 v134, v98, v99
	v_cvt_pk_bf16_f32 v135, v100, v101
	ds_read_b64_tr_b16 v[98:99], v174 offset:38912
	ds_read_b64_tr_b16 v[100:101], v174 offset:39424
	s_waitcnt lgkmcnt(10)
	v_mfma_f32_32x32x16_bf16 v[66:81], v[210:213], v[150:153], v[66:81]
	v_add_f32_e32 v130, v104, v130
	v_add_f32_e32 v130, v105, v130
	v_add_f32_e32 v130, v106, v130
	v_add_f32_e32 v130, v107, v130
	v_cvt_pk_bf16_f32 v136, v102, v103
	v_cvt_pk_bf16_f32 v137, v104, v105
	ds_read_b64_tr_b16 v[102:103], v174 offset:35840
	ds_read_b64_tr_b16 v[104:105], v174 offset:36352
	s_waitcnt lgkmcnt(7)
	v_mfma_f32_32x32x16_bf16 v[82:97], v[162:165], v[146:149], v[82:97]
	v_add_f32_e32 v130, v108, v130
	v_add_f32_e32 v130, v109, v130
	v_add_f32_e32 v130, v110, v130
	v_add_f32_e32 v175, v111, v130
	v_cvt_pk_bf16_f32 v130, v106, v107
	v_cvt_pk_bf16_f32 v131, v108, v109
	ds_read_b64_tr_b16 v[106:107], v174 offset:39936
	ds_read_b64_tr_b16 v[108:109], v174 offset:40448
	s_waitcnt lgkmcnt(8)
	v_mfma_f32_32x32x16_bf16 v[66:81], v[166:169], v[146:149], v[66:81]
	v_add_f32_e32 v132, v112, v175
	v_add_f32_e32 v132, v113, v132
	v_add_f32_e32 v162, 0, v132
	v_cvt_pk_bf16_f32 v132, v110, v111
	v_cvt_pk_bf16_f32 v133, v112, v113
	s_add_u32 s6, s87, 0xa0000
	s_addc_u32 s7, s88, 0
	s_add_i32 s12, s54, s33
	s_mov_b32 m0, s12
	s_nop 0
	global_load_lds_dwordx4 v202, s[6:7]
	s_add_u32 s6, s85, 0x22060000
	s_addc_u32 s7, s86, 0
	s_add_i32 s12, s83, s59
	s_add_u32 s54, s85, 0x22060080
	s_mov_b32 m0, s12
	s_nop 0
	global_load_lds_dwordx4 v203, s[6:7]
	s_addc_u32 s55, s86, 0
	s_addk_i32 s12, 0x2000
	s_cmp_ge_i32 s89, s57
	s_cselect_b64 s[86:87], -1, 0
	s_cmp_lt_i32 s89, s60
	s_cselect_b64 s[6:7], -1, 0
	s_mov_b32 m0, s12
	s_nop 0
	global_load_lds_dwordx4 v203, s[54:55]
	s_and_b64 s[86:87], s[86:87], s[6:7]
	s_andn2_b64 vcc, exec, s[86:87]
	s_cbranch_vccnz .LBB0_1094
	ds_read2_b32 v[110:111], v179 offset0:64 offset1:65
	ds_read2_b32 v[112:113], v179 offset0:66 offset1:67
	ds_read2_b32 v[164:165], v179 offset0:72 offset1:73
	ds_read2_b32 v[166:167], v179 offset0:74 offset1:75
	ds_read2_b32 v[168:169], v179 offset0:80 offset1:81
	ds_read2_b32 v[176:177], v179 offset0:82 offset1:83
	ds_read2_b32 v[180:181], v179 offset0:88 offset1:89
	ds_read2_b32 v[206:207], v179 offset0:90 offset1:91
	ds_read2_b32 v[208:209], v179 offset0:96 offset1:97
	ds_read2_b32 v[210:211], v179 offset0:98 offset1:99
	ds_read2_b32 v[212:213], v179 offset0:104 offset1:105
	ds_read2_b32 v[214:215], v179 offset0:106 offset1:107
	s_waitcnt lgkmcnt(11)
	v_pk_add_f32 v[82:83], v[82:83], v[110:111]
	s_waitcnt lgkmcnt(5)
	v_pk_add_f32 v[94:95], v[94:95], v[180:181]
	v_pk_add_f32 v[92:93], v[92:93], v[176:177]
	v_pk_add_f32 v[90:91], v[90:91], v[168:169]
	ds_read2_b32 v[110:111], v179 offset0:112 offset1:113
	ds_read2_b32 v[168:169], v179 offset0:114 offset1:115
	ds_read2_b32 v[176:177], v179 offset0:120 offset1:121
	ds_read2_b32 v[180:181], v179 offset0:122 offset1:123
	s_waitcnt lgkmcnt(8)
	v_pk_add_f32 v[96:97], v[96:97], v[206:207]
	v_pk_add_f32 v[88:89], v[88:89], v[166:167]
	v_pk_add_f32 v[86:87], v[86:87], v[164:165]
	v_pk_add_f32 v[84:85], v[84:85], v[112:113]
	s_waitcnt lgkmcnt(7)
	v_pk_add_f32 v[66:67], v[66:67], v[208:209]
	s_waitcnt lgkmcnt(0)
	v_pk_add_f32 v[80:81], v[80:81], v[180:181]
	v_pk_add_f32 v[78:79], v[78:79], v[176:177]
	v_pk_add_f32 v[76:77], v[76:77], v[168:169]
	v_pk_add_f32 v[74:75], v[74:75], v[110:111]
	v_pk_add_f32 v[72:73], v[72:73], v[214:215]
	v_pk_add_f32 v[70:71], v[70:71], v[212:213]
	v_pk_add_f32 v[68:69], v[68:69], v[210:211]

.LBB0_1100:
	v_add_u32_e32 v179, s11, v204
	ds_read_b64_tr_b16 v[174:175], v179 offset:32768
	ds_read_b64_tr_b16 v[176:177], v179 offset:33280
	s_add_i32 s6, s82, 0xffffe000
	s_and_b32 s92, s6, 0x6000
	v_add_u32_e32 v0, s92, v201
	s_waitcnt lgkmcnt(5)
	v_mfma_f32_32x32x16_bf16 v[114:129], v[114:117], v[158:161], 0
	v_add_f32_e32 v98, v82, v83
	v_add_f32_e32 v98, v84, v98
	v_add_f32_e32 v98, v85, v98
	v_add_f32_e32 v98, v86, v98
	v_add_f32_e32 v98, v87, v98
	v_cvt_pk_bf16_f32 v142, v82, v83
	v_cvt_pk_bf16_f32 v143, v84, v85
	ds_read_b64_tr_b16 v[82:83], v179 offset:36864
	ds_read_b64_tr_b16 v[84:85], v179 offset:37376
	v_add_f32_e32 v98, v88, v98
	v_add_f32_e32 v98, v89, v98
	v_add_f32_e32 v98, v90, v98
	v_add_f32_e32 v130, v91, v98
	s_waitcnt lgkmcnt(6)
	v_mfma_f32_32x32x16_bf16 v[98:113], v[170:173], v[158:161], 0
	v_cvt_pk_bf16_f32 v144, v86, v87
	v_cvt_pk_bf16_f32 v145, v88, v89
	ds_read_b128 v[170:173], v0 offset:4096
	ds_read_b128 v[206:209], v0 offset:4608
	ds_read_b64_tr_b16 v[86:87], v179 offset:33792
	ds_read_b64_tr_b16 v[88:89], v179 offset:34304
	s_waitcnt lgkmcnt(9)
	v_mfma_f32_32x32x16_bf16 v[114:129], v[166:169], v[154:157], v[114:129]
	v_add_f32_e32 v130, v92, v130
	v_add_f32_e32 v130, v93, v130
	v_add_f32_e32 v130, v94, v130
	v_add_f32_e32 v130, v95, v130
	v_cvt_pk_bf16_f32 v138, v90, v91
	v_cvt_pk_bf16_f32 v139, v92, v93
	ds_read_b64_tr_b16 v[90:91], v179 offset:37888
	ds_read_b64_tr_b16 v[92:93], v179 offset:38400
	s_waitcnt lgkmcnt(10)
	v_mfma_f32_32x32x16_bf16 v[98:113], v[162:165], v[154:157], v[98:113]
	v_add_f32_e32 v130, v96, v130
	v_add_f32_e32 v130, v97, v130
	v_add_f32_e32 v130, v66, v130
	v_add_f32_e32 v130, v67, v130
	v_cvt_pk_bf16_f32 v140, v94, v95
	v_cvt_pk_bf16_f32 v141, v96, v97
	ds_read_b128 v[162:165], v0 offset:6144
	ds_read_b128 v[166:169], v0 offset:6656
	ds_read_b64_tr_b16 v[94:95], v179 offset:34816
	ds_read_b64_tr_b16 v[96:97], v179 offset:35328
	s_waitcnt lgkmcnt(9)
	v_mfma_f32_32x32x16_bf16 v[114:129], v[170:173], v[150:153], v[114:129]
	v_add_f32_e32 v0, v68, v130
	v_add_f32_e32 v0, v69, v0
	v_add_f32_e32 v0, v70, v0
	v_add_f32_e32 v0, v71, v0
	v_cvt_pk_bf16_f32 v134, v66, v67
	v_cvt_pk_bf16_f32 v135, v68, v69
	ds_read_b64_tr_b16 v[66:67], v179 offset:38912
	ds_read_b64_tr_b16 v[68:69], v179 offset:39424
	s_waitcnt lgkmcnt(10)
	v_mfma_f32_32x32x16_bf16 v[98:113], v[206:209], v[150:153], v[98:113]
	v_add_f32_e32 v0, v72, v0
	v_add_f32_e32 v0, v73, v0
	v_add_f32_e32 v0, v74, v0
	v_add_f32_e32 v0, v75, v0
	v_cvt_pk_bf16_f32 v136, v70, v71
	v_cvt_pk_bf16_f32 v137, v72, v73
	ds_read_b64_tr_b16 v[70:71], v179 offset:35840
	ds_read_b64_tr_b16 v[72:73], v179 offset:36352
	s_waitcnt lgkmcnt(7)
	v_mfma_f32_32x32x16_bf16 v[114:129], v[162:165], v[146:149], v[114:129]
	v_add_f32_e32 v0, v76, v0
	v_add_f32_e32 v0, v77, v0
	v_add_f32_e32 v0, v78, v0
	v_add_f32_e32 v0, v79, v0
	v_cvt_pk_bf16_f32 v130, v74, v75
	v_cvt_pk_bf16_f32 v131, v76, v77
	ds_read_b64_tr_b16 v[74:75], v179 offset:39936
	ds_read_b64_tr_b16 v[76:77], v179 offset:40448
	s_waitcnt lgkmcnt(8)
	v_mfma_f32_32x32x16_bf16 v[98:113], v[166:169], v[146:149], v[98:113]
	v_add_f32_e32 v0, v80, v0
	v_add_f32_e32 v0, v81, v0
	v_add_f32_e32 v0, 0, v0
	v_cvt_pk_bf16_f32 v132, v78, v79
	v_cvt_pk_bf16_f32 v133, v80, v81
	s_add_i32 s90, s84, 2
	s_cmp_ge_u32 s90, s69
	s_cselect_b64 s[10:11], -1, 0
	s_and_b64 vcc, exec, s[10:11]
	s_cbranch_vccnz .LBB0_1102
	s_add_i32 s6, s82, 0x4000
	s_and_b32 s6, s6, 0x6000
	s_add_i32 s12, s6, s33
	s_add_u32 s6, s86, s8
	s_addc_u32 s7, s87, s9
	s_add_u32 s6, s6, 0x80000
	s_addc_u32 s7, s7, 0
	s_mov_b32 m0, s12
	s_nop 0
	global_load_lds_dwordx4 v202, s[6:7]
.LBB0_1102:
	s_add_i32 s91, s84, -1
	s_add_u32 s95, s88, s8
	s_addc_u32 s96, s89, s9
	s_add_u32 s6, s95, 0x22040000
	s_addc_u32 s7, s96, 0
	s_add_i32 s12, s85, s59
	s_add_u32 s42, s95, 0x22040080
	s_mov_b32 m0, s12
	s_nop 0
	global_load_lds_dwordx4 v203, s[6:7]
	s_addc_u32 s43, s96, 0
	s_addk_i32 s12, 0x2000
	s_cmp_ge_i32 s91, s57
	s_cselect_b64 s[54:55], -1, 0
	s_cmp_lt_i32 s91, s60
	s_cselect_b64 s[6:7], -1, 0
	s_mov_b32 m0, s12
	s_nop 0
	global_load_lds_dwordx4 v203, s[42:43]
	s_and_b64 s[54:55], s[54:55], s[6:7]
	s_andn2_b64 vcc, exec, s[54:55]
	s_cbranch_vccnz .LBB0_1104
	ds_read2_b32 v[78:79], v205 offset1:1
	ds_read2_b32 v[80:81], v205 offset0:2 offset1:3
	ds_read2_b32 v[162:163], v205 offset0:8 offset1:9
	ds_read2_b32 v[164:165], v205 offset0:10 offset1:11
	ds_read2_b32 v[166:167], v205 offset0:16 offset1:17
	ds_read2_b32 v[168:169], v205 offset0:18 offset1:19
	ds_read2_b32 v[170:171], v205 offset0:24 offset1:25
	ds_read2_b32 v[172:173], v205 offset0:26 offset1:27
	ds_read2_b32 v[180:181], v205 offset0:32 offset1:33
	ds_read2_b32 v[206:207], v205 offset0:34 offset1:35
	ds_read2_b32 v[208:209], v205 offset0:40 offset1:41
	ds_read2_b32 v[210:211], v205 offset0:42 offset1:43
	s_waitcnt lgkmcnt(11)
	v_pk_add_f32 v[114:115], v[114:115], v[78:79]
	s_waitcnt lgkmcnt(5)
	v_pk_add_f32 v[126:127], v[126:127], v[170:171]
	v_pk_add_f32 v[124:125], v[124:125], v[168:169]
	v_pk_add_f32 v[122:123], v[122:123], v[166:167]
	ds_read2_b32 v[78:79], v205 offset0:48 offset1:49
	ds_read2_b32 v[166:167], v205 offset0:50 offset1:51
	ds_read2_b32 v[168:169], v205 offset0:56 offset1:57
	ds_read2_b32 v[170:171], v205 offset0:58 offset1:59
	s_waitcnt lgkmcnt(8)
	v_pk_add_f32 v[128:129], v[128:129], v[172:173]
	v_pk_add_f32 v[120:121], v[120:121], v[164:165]
	v_pk_add_f32 v[118:119], v[118:119], v[162:163]
	v_pk_add_f32 v[116:117], v[116:117], v[80:81]
	s_waitcnt lgkmcnt(7)
	v_pk_add_f32 v[98:99], v[98:99], v[180:181]
	s_waitcnt lgkmcnt(0)
	v_pk_add_f32 v[112:113], v[112:113], v[170:171]
	v_pk_add_f32 v[110:111], v[110:111], v[168:169]
	v_pk_add_f32 v[108:109], v[108:109], v[166:167]
	v_pk_add_f32 v[106:107], v[106:107], v[78:79]
	v_pk_add_f32 v[104:105], v[104:105], v[210:211]
	v_pk_add_f32 v[102:103], v[102:103], v[208:209]
	v_pk_add_f32 v[100:101], v[100:101], v[206:207]

.LBB0_1114:
	v_add_u32_e32 v208, s83, v204
	ds_read_b64_tr_b16 v[174:175], v208 offset:32768
	ds_read_b64_tr_b16 v[176:177], v208 offset:33280
	s_waitcnt lgkmcnt(5)
	v_mfma_f32_32x32x16_bf16 v[82:97], v[70:73], v[158:161], 0
	v_add_f32_e32 v74, v114, v115
	v_add_f32_e32 v74, v116, v74
	v_add_f32_e32 v74, v117, v74
	v_add_f32_e32 v74, v118, v74
	v_add_f32_e32 v74, v119, v74
	v_cvt_pk_bf16_f32 v142, v114, v115
	v_cvt_pk_bf16_f32 v143, v116, v117
	ds_read_b64_tr_b16 v[178:179], v208 offset:36864
	ds_read_b64_tr_b16 v[180:181], v208 offset:37376
	v_add_f32_e32 v70, v120, v74
	v_add_f32_e32 v70, v121, v70
	v_add_f32_e32 v70, v122, v70
	v_add_f32_e32 v130, v123, v70
	s_waitcnt lgkmcnt(6)
	v_mfma_f32_32x32x16_bf16 v[66:81], v[66:69], v[158:161], 0
	v_cvt_pk_bf16_f32 v144, v118, v119
	v_cvt_pk_bf16_f32 v145, v120, v121
	ds_read_b128 v[114:117], v207 offset:4096
	ds_read_b128 v[170:173], v207 offset:4608
	ds_read_b64_tr_b16 v[118:119], v208 offset:33792
	ds_read_b64_tr_b16 v[120:121], v208 offset:34304
	s_waitcnt lgkmcnt(9)
	v_mfma_f32_32x32x16_bf16 v[82:97], v[166:169], v[154:157], v[82:97]
	v_add_f32_e32 v130, v124, v130
	v_add_f32_e32 v130, v125, v130
	v_add_f32_e32 v130, v126, v130
	v_add_f32_e32 v130, v127, v130
	v_cvt_pk_bf16_f32 v138, v122, v123
	v_cvt_pk_bf16_f32 v139, v124, v125
	ds_read_b64_tr_b16 v[122:123], v208 offset:37888
	ds_read_b64_tr_b16 v[124:125], v208 offset:38400
	s_waitcnt lgkmcnt(10)
	v_mfma_f32_32x32x16_bf16 v[66:81], v[162:165], v[154:157], v[66:81]
	v_add_f32_e32 v130, v128, v130
	v_add_f32_e32 v130, v129, v130
	v_add_f32_e32 v130, v98, v130
	v_add_f32_e32 v130, v99, v130
	v_cvt_pk_bf16_f32 v140, v126, v127
	v_cvt_pk_bf16_f32 v141, v128, v129
	ds_read_b128 v[166:169], v207 offset:6144
	ds_read_b128 v[162:165], v207 offset:6656
	ds_read_b64_tr_b16 v[126:127], v208 offset:34816
	ds_read_b64_tr_b16 v[128:129], v208 offset:35328
	s_waitcnt lgkmcnt(9)
	v_mfma_f32_32x32x16_bf16 v[82:97], v[114:117], v[150:153], v[82:97]
	v_add_f32_e32 v130, v100, v130
	v_add_f32_e32 v130, v101, v130
	v_add_f32_e32 v130, v102, v130
	v_add_f32_e32 v130, v103, v130
	v_cvt_pk_bf16_f32 v134, v98, v99
	v_cvt_pk_bf16_f32 v135, v100, v101
	ds_read_b64_tr_b16 v[98:99], v208 offset:38912
	ds_read_b64_tr_b16 v[100:101], v208 offset:39424
	s_waitcnt lgkmcnt(10)
	v_mfma_f32_32x32x16_bf16 v[66:81], v[170:173], v[150:153], v[66:81]
	v_add_f32_e32 v130, v104, v130
	v_add_f32_e32 v130, v105, v130
	v_add_f32_e32 v130, v106, v130
	v_add_f32_e32 v130, v107, v130
	v_cvt_pk_bf16_f32 v136, v102, v103
	v_cvt_pk_bf16_f32 v137, v104, v105
	ds_read_b64_tr_b16 v[102:103], v208 offset:35840
	ds_read_b64_tr_b16 v[104:105], v208 offset:36352
	s_waitcnt lgkmcnt(7)
	v_mfma_f32_32x32x16_bf16 v[82:97], v[166:169], v[146:149], v[82:97]
	v_add_f32_e32 v130, v108, v130
	v_add_f32_e32 v130, v109, v130
	v_add_f32_e32 v130, v110, v130
	v_add_f32_e32 v207, v111, v130
	v_cvt_pk_bf16_f32 v130, v106, v107
	v_cvt_pk_bf16_f32 v131, v108, v109
	ds_read_b64_tr_b16 v[106:107], v208 offset:39936
	ds_read_b64_tr_b16 v[108:109], v208 offset:40448
	s_waitcnt lgkmcnt(8)
	v_mfma_f32_32x32x16_bf16 v[66:81], v[162:165], v[146:149], v[66:81]
	v_add_f32_e32 v132, v112, v207
	v_add_f32_e32 v132, v113, v132
	v_add_f32_e32 v207, 0, v132
	v_cvt_pk_bf16_f32 v132, v110, v111
	v_cvt_pk_bf16_f32 v133, v112, v113
	s_add_i32 s6, s84, 3
	s_cmp_ge_u32 s6, s69
	s_cselect_b64 s[42:43], -1, 0
	s_and_b64 vcc, exec, s[42:43]
	s_cbranch_vccnz .LBB0_1116
	s_add_i32 s12, s92, s33
	s_add_u32 s6, s86, s8
	s_addc_u32 s7, s87, s9
	s_add_u32 s6, s6, 0xa0000
	s_addc_u32 s7, s7, 0
	s_mov_b32 m0, s12
	s_nop 0
	global_load_lds_dwordx4 v202, s[6:7]
.LBB0_1116:
	s_add_i32 s6, s85, 0x4000
	s_cmpk_lg_u32 s85, 0x8000
	s_cselect_b32 s83, s6, 0
	s_add_i32 s6, s84, 1
	s_cmp_lt_u32 s6, s69
	s_cselect_b64 s[54:55], -1, 0
	s_cmp_ge_u32 s6, s69
	s_cbranch_scc1 .LBB0_1118
	s_add_u32 s6, s95, 0x22060000
	s_addc_u32 s7, s96, 0
	s_add_u32 s12, s95, 0x22060080
	s_addc_u32 s13, s96, 0
	s_add_i32 s14, s83, s59
	s_mov_b32 m0, s14
	s_nop 0
	global_load_lds_dwordx4 v203, s[6:7]
	s_add_i32 s6, s14, 0x2000
	s_mov_b32 m0, s6
	s_nop 0
	global_load_lds_dwordx4 v203, s[12:13]

; #define WAIT_BAR(N) asm volatile("s_waitcnt vmcnt(" #N ") lgkmcnt(0)\n\ts_barrier":::"memory")
;   #define DMA_K(t,slot) glds16s(Kb+(long)(t)*KVBLK*kp,ksrc,(unsigned)__builtin_amdgcn_readfirstlane(kdst+(slot)))
;   #define DMA_V(t,slot) do{ glds16s(Vb+(long)(t)*KVBLK*vp,vsrc,(unsigned)__builtin_amdgcn_readfirstlane(vdst+(slot))); \
;       if(VH==2) glds16s(Vb+(long)(t)*KVBLK*vp+64,vsrc,(unsigned)__builtin_amdgcn_readfirstlane(vdst+(slot)+8192)); }while(0)
; template<int VH,bool HAS_BIAS,int MODE> __device__ __forceinline__ void attn_unit2(const bf16*Qb,int qp,const bf16*__restrict__ Kb,int kp,const bf16*__restrict__ Vb,int vp,bf16*Ob,int op,int q0,int NT,const float*relb,char*shm,float lam,const float*subg,float gmul){
;     ...
;   const unsigned ksrc=(unsigned)(lane*kp+wid*8)*2u;
;   const unsigned vsrc=(unsigned)((16*(wid&3)+(lane>>2))*vp+(wid>>2)*32+(lane&3)*8)*2u;
;   const unsigned kdst=lds0+LM::L_K+wid*1024, vdst=lds0+LM::L_V+wid*1024;
;     ...
;   const int vb0=(int)(lds0+LM::L_V)+((lane>>4)&1)*32+(lane&3)*8+(4*hi+((lane&15)>>2))*64;
;   const lds_cptr kp0=shm3+LM::L_K+hi*1024+r32*16;
;   const lds_cptr vp0=shm3+LM::L_V+((lane>>4)&1)*32+(lane&3)*8+(4*hi+((lane&15)>>2))*64;
;   const int qw_=q0+32*wid; const int tn0=HAS_BIAS?(qw_>=90?((qw_-90)>>6):0):0, tn1=HAS_BIAS?(((qw_+185)>>6)<NT?((qw_+185)>>6):NT):0;
;   float cb=0.f,ca=0.f;
;   typedef __attribute__((address_space(3))) float lds_f32;
;   typedef __attribute__((address_space(3))) char* lds_ptr_;
;   lds_f32* btab=(lds_f32*)((lds_ptr_)shm)+LM::L_BT/4;
;   if(HAS_BIAS){ const float L2E=1.4426950408889634f; cb=L2E*relb[15*8]; ca=L2E*relb[31*8];
;     for(int i=tid;i<768;i+=512){ const int rel=i-384; const int n=rel<0?-rel:rel; int bk=n<8?n:(8+(31-__builtin_clz((unsigned)(n*n)))-6); if(n>=8&&bk>15)bk=15; if(rel>0)bk+=16; btab[i]=L2E*relb[bk*8]; } }
;   const int lanebias=-q0-32*wid-r32+4*hi+384;
;     ...
;   DMA_K(0,0);DMA_V(0,0);DMA_K(1,KSL);
;   bf16x8 qr[4];
;   #pragma unroll
;   for(int d0=0;d0<4;++d0)qr[d0]=*reinterpret_cast<const bf16x8*>(&Qw[(long)r32*qp+d0*16+hi*8]);
;   DMA_K(2,2*KSL);
;   float l_reg=0.f;f32x16 o[2*VH];
;   #pragma unroll
;   for(int d_=0;d_<2*VH;++d_)o[d_]=f32x16{};
;   const f32x16 zero16=f32x16{};
;   f32x16 pA0,pA1,pB0,pB1; bf16x8 kf[4];
;   int sv_prev=0,sv_cur=0,sv_next=VSL;
;     ...
;   if(VH==1){WAIT_BAR(3);}else{WAIT_BAR(4);}
;   qkt(pA0,pA1,shm+LM::L_K,qr,zero16,r32,hi);
;   BIASADD(pA0,pA1,0);
.LBB0_1153:
	s_or_b64 exec, exec, s[54:55]
	s_add_u32 s8, s44, 0x80
	s_addc_u32 s9, s45, 0
	s_ashr_i32 s54, s81, 6
	s_lshl_b32 s6, s54, 5
	s_add_i32 s6, s6, s77
	s_ashr_i32 s7, s6, 31
	s_lshl_b64 s[10:11], s[6:7], 11
	s_add_u32 s12, s75, s10
	v_and_b32_e32 v197, 63, v184
	s_addc_u32 s13, s76, s11
	s_lshl_b32 s7, s54, 4
	v_bfe_u32 v2, v184, 2, 4
	v_lshl_add_u32 v206, v197, 11, s7
	v_and_or_b32 v2, s7, 48, v2
	s_ashr_i32 s7, s81, 3
	s_and_b32 s7, s7, 0x7fffffe0
	v_lshl_add_u32 v2, v2, 10, s7
	s_lshl_b32 s7, s54, 10
	s_cmp_lg_u32 0, -1
	s_cselect_b32 s14, 0, 0
	s_add_i32 s33, s7, s14
	s_add_i32 s14, s6, 0xffffffa6
	s_add_i32 s57, s33, 0x8000
	s_ashr_i32 s14, s14, 6
	v_lshlrev_b32_e32 v3, 3, v184
	s_cmpk_gt_i32 s6, 0x59
	v_and_b32_e32 v199, 24, v3
	s_cselect_b32 s55, s14, 0
	s_add_i32 s14, s6, 0xb9
	v_or_b32_e32 v2, v2, v199
	s_ashr_i32 s56, s14, 6
	s_mov_b32 m0, s33
	s_nop 0
	global_load_lds_dwordx4 v206, s[8:9]
	v_lshlrev_b32_e32 v207, 1, v2
	s_mov_b32 m0, s57
	s_nop 0
	global_load_lds_dwordx4 v207, s[46:47]
	v_and_b32_e32 v185, 31, v184
	s_add_i32 s14, s33, 0xa000
	v_bfe_u32 v35, v184, 5, 1
	s_mov_b32 m0, s14
	s_nop 0
	global_load_lds_dwordx4 v207, s[48:49]
	s_add_u32 s40, s44, 0x20080
	v_lshlrev_b32_e32 v2, 11, v185
	s_addc_u32 s41, s45, 0
	s_add_i32 s14, s33, 0x2000
	s_mov_b32 m0, s14
	s_nop 0
	global_load_lds_dwordx4 v206, s[40:41]
	v_lshl_or_b32 v2, v35, 4, v2
	global_load_dwordx4 v[158:161], v2, s[12:13] offset:128
	global_load_dwordx4 v[154:157], v2, s[12:13] offset:160
	global_load_dwordx4 v[150:153], v2, s[12:13] offset:192
	global_load_dwordx4 v[146:149], v2, s[12:13] offset:224
	s_add_u32 s12, s44, 0x40080
	v_lshlrev_b32_e32 v194, 10, v35
	v_lshlrev_b32_e32 v2, 4, v185
	s_addc_u32 s13, s45, 0
	s_add_i32 s14, s33, 0x4000
	s_mov_b32 m0, s14
	s_nop 0
	global_load_lds_dwordx4 v206, s[12:13]
	v_add3_u32 v205, 0, v194, v2
	s_waitcnt vmcnt(4) lgkmcnt(0)
	s_barrier
	ds_read_b128 v[2:5], v205
	ds_read_b128 v[18:21], v205 offset:512
	ds_read_b128 v[36:39], v205 offset:2048
	s_cmp_lt_i32 s55, 1
	s_cselect_b64 s[12:13], -1, 0
	s_cmp_gt_i32 s56, 0
	s_cselect_b64 s[40:41], -1, 0
	s_and_b64 s[12:13], s[12:13], s[40:41]
	v_lshlrev_b32_e32 v198, 2, v35
	v_or_b32_e32 v204, s6, v185
	s_and_b64 vcc, exec, s[12:13]
	s_waitcnt vmcnt(3) lgkmcnt(0)
	v_mfma_f32_32x32x16_bf16 v[2:17], v[2:5], v[158:161], 0
	s_waitcnt vmcnt(2)
	v_mfma_f32_32x32x16_bf16 v[2:17], v[36:39], v[154:157], v[2:17]
	ds_read_b128 v[36:39], v205 offset:2560
	v_mfma_f32_32x32x16_bf16 v[18:33], v[18:21], v[158:161], 0
	s_waitcnt lgkmcnt(0)
	v_mfma_f32_32x32x16_bf16 v[18:33], v[36:39], v[154:157], v[18:33]
	ds_read_b128 v[36:39], v205 offset:4096
	s_waitcnt vmcnt(1) lgkmcnt(0)
	v_mfma_f32_32x32x16_bf16 v[2:17], v[36:39], v[150:153], v[2:17]
	ds_read_b128 v[36:39], v205 offset:4608
	s_waitcnt lgkmcnt(0)
	v_mfma_f32_32x32x16_bf16 v[18:33], v[36:39], v[150:153], v[18:33]
	ds_read_b128 v[36:39], v205 offset:6144
	s_waitcnt vmcnt(0) lgkmcnt(0)
	v_mfma_f32_32x32x16_bf16 v[2:17], v[36:39], v[146:149], v[2:17]
	ds_read_b128 v[36:39], v205 offset:6656
	s_waitcnt lgkmcnt(0)
	v_mfma_f32_32x32x16_bf16 v[18:33], v[36:39], v[146:149], v[18:33]
	s_cbranch_vccz .LBB0_1155
	v_or_b32_e32 v36, 0x180, v198
	v_sub_u32_e32 v36, v36, v204
	v_lshl_add_u32 v36, v36, 2, 0
	v_add_u32_e32 v60, 0x14800, v36
	ds_read2_b32 v[36:37], v60 offset1:1
	ds_read2_b32 v[38:39], v60 offset0:2 offset1:3
	ds_read2_b32 v[40:41], v60 offset0:8 offset1:9
	ds_read2_b32 v[42:43], v60 offset0:10 offset1:11
	ds_read2_b32 v[44:45], v60 offset0:16 offset1:17
	ds_read2_b32 v[46:47], v60 offset0:18 offset1:19
	ds_read2_b32 v[48:49], v60 offset0:24 offset1:25
	ds_read2_b32 v[50:51], v60 offset0:26 offset1:27
	ds_read2_b32 v[52:53], v60 offset0:32 offset1:33
	ds_read2_b32 v[54:55], v60 offset0:34 offset1:35
	ds_read2_b32 v[56:57], v60 offset0:40 offset1:41
	ds_read2_b32 v[58:59], v60 offset0:42 offset1:43
	s_waitcnt lgkmcnt(4)
	v_pk_add_f32 v[16:17], v[16:17], v[50:51]
	v_pk_add_f32 v[14:15], v[14:15], v[48:49]
	v_pk_add_f32 v[12:13], v[12:13], v[46:47]
	v_pk_add_f32 v[10:11], v[10:11], v[44:45]
	ds_read2_b32 v[44:45], v60 offset0:48 offset1:49
	ds_read2_b32 v[46:47], v60 offset0:50 offset1:51
	ds_read2_b32 v[48:49], v60 offset0:56 offset1:57
	ds_read2_b32 v[50:51], v60 offset0:58 offset1:59
	v_pk_add_f32 v[8:9], v[8:9], v[42:43]
	v_pk_add_f32 v[6:7], v[6:7], v[40:41]
	v_pk_add_f32 v[4:5], v[4:5], v[38:39]
	v_pk_add_f32 v[2:3], v[2:3], v[36:37]
	s_waitcnt lgkmcnt(0)
	v_pk_add_f32 v[32:33], v[32:33], v[50:51]
	v_pk_add_f32 v[30:31], v[30:31], v[48:49]
	v_pk_add_f32 v[28:29], v[28:29], v[46:47]
	v_pk_add_f32 v[26:27], v[26:27], v[44:45]
	v_pk_add_f32 v[24:25], v[24:25], v[58:59]
	v_pk_add_f32 v[22:23], v[22:23], v[56:57]
	v_pk_add_f32 v[20:21], v[20:21], v[54:55]
	v_pk_add_f32 v[18:19], v[18:19], v[52:53]
; #define WAIT_BAR(N) asm volatile("s_waitcnt vmcnt(" #N ") lgkmcnt(0)\n\ts_barrier":::"memory")
;   #define DMA_K(t,slot) glds16s(Kb+(long)(t)*KVBLK*kp,ksrc,(unsigned)__builtin_amdgcn_readfirstlane(kdst+(slot)))
;   #define DMA_V(t,slot) do{ glds16s(Vb+(long)(t)*KVBLK*vp,vsrc,(unsigned)__builtin_amdgcn_readfirstlane(vdst+(slot))); \
;       if(VH==2) glds16s(Vb+(long)(t)*KVBLK*vp+64,vsrc,(unsigned)__builtin_amdgcn_readfirstlane(vdst+(slot)+8192)); }while(0)
;   #define BIASADD(P0,P1,t) do{ if(HAS_BIAS&&(t)>=tn0&&(t)<tn1){ const lds_f32*bp_=btab+(64*(t)+lanebias); \
;     _Pragma("unroll") for(int r=0;r<16;++r){ P0[r]+=bp_[(r&3)+8*(r>>2)]; P1[r]+=bp_[(r&3)+8*(r>>2)+32]; } } }while(0)
;   #define ROT() do{sv_prev=sv_cur;sv_cur=sv_next;sv_next=(sv_next==2*VSL)?0:sv_next+VSL;}while(0)
;   #define KPRE(tn) do{ const lds_cptr kn_=kp0+(((tn)&3)*KSL); kf[0]=KLD(kn_); kf[1]=KLD(kn_+512); kf[2]=KLD(kn_+2048); kf[3]=KLD(kn_+2560); }while(0)
; template<int VH,bool HAS_BIAS,int MODE> __device__ __forceinline__ void attn_unit2(const bf16*Qb,int qp,const bf16*__restrict__ Kb,int kp,const bf16*__restrict__ Vb,int vp,bf16*Ob,int op,int q0,int NT,const float*relb,char*shm,float lam,const float*subg,float gmul){
;     ...
;   float l_reg=0.f;f32x16 o[2*VH];
;   #pragma unroll
;   for(int d_=0;d_<2*VH;++d_)o[d_]=f32x16{};
;   const f32x16 zero16=f32x16{};
;   f32x16 pA0,pA1,pB0,pB1; bf16x8 kf[4];
;   int sv_prev=0,sv_cur=0,sv_next=VSL;
;     ...
;   if(VH==1){WAIT_BAR(3);}else{WAIT_BAR(4);}
;   qkt(pA0,pA1,shm+LM::L_K,qr,zero16,r32,hi);
;   BIASADD(pA0,pA1,0);
;   _Pragma("unroll") for(int r=0;r<16;++r){pA0[r]=__builtin_amdgcn_exp2f(pA0[r]);pA1[r]=__builtin_amdgcn_exp2f(pA1[r]);}
;   WAIT_BAR(0);
;   DMA_K(3,3*KSL);DMA_V(1,VSL);
;   ROT();
;   KPRE(1);
;   s16x4 vlo[8],vhi[8]; u32x4 pw0,pw1,pw2,pw3;
.LBB0_1155:
	s_min_i32 s48, s56, s69
	s_add_u32 s12, s8, 0x60000
	s_addc_u32 s13, s9, 0
	s_cmp_lg_u32 0, -1
	s_cselect_b32 s14, 0, 0
	s_waitcnt vmcnt(0) lgkmcnt(0)
	s_barrier
	s_add_i32 s7, s14, s7
	s_add_i32 s14, s7, 0x6000
	s_mov_b32 m0, s14
	s_nop 0
	global_load_lds_dwordx4 v206, s[12:13]
	s_add_i32 s12, s7, 0xc000
	s_mov_b32 m0, s12
	s_nop 0
	global_load_lds_dwordx4 v207, s[50:51]
	s_add_i32 s7, s7, 0xe000
	s_mov_b32 m0, s7
	s_nop 0
	global_load_lds_dwordx4 v207, s[52:53]
	v_lshlrev_b32_e32 v36, 1, v197
	v_mul_f32_e32 v202, 0x3fb8aa3b, v0
	ds_read_b128 v[162:165], v205 offset:10752
	ds_read_b128 v[166:169], v205 offset:10240
	ds_read_b128 v[170:173], v205 offset:8704
	ds_read_b128 v[114:117], v205 offset:8192
	v_lshlrev_b32_e32 v0, 4, v35
	v_lshlrev_b32_e32 v196, 2, v185
	v_and_b32_e32 v200, 32, v36
	v_bfe_u32 v36, v184, 2, 2
	v_sub_u32_e32 v0, v0, v196
	s_lshl_b32 s7, s54, 7
	v_or_b32_e32 v36, v198, v36
	v_subrev_u32_e32 v0, s7, v0
	v_lshlrev_b32_e32 v201, 6, v36
	v_add_u32_e32 v36, 0, v200
	v_exp_f32_e32 v66, v18
	v_exp_f32_e32 v67, v19
	v_exp_f32_e32 v68, v20
	v_exp_f32_e32 v69, v21
	v_exp_f32_e32 v70, v22
	v_exp_f32_e32 v71, v23
	v_exp_f32_e32 v72, v24
	v_exp_f32_e32 v73, v25
	v_exp_f32_e32 v74, v26
	v_exp_f32_e32 v75, v27
	v_exp_f32_e32 v76, v28
	v_exp_f32_e32 v77, v29
	v_exp_f32_e32 v78, v30
	v_exp_f32_e32 v79, v31
	v_exp_f32_e32 v80, v32
	v_exp_f32_e32 v81, v33
	v_exp_f32_e32 v82, v2
	v_exp_f32_e32 v83, v3
	v_exp_f32_e32 v84, v4
	v_exp_f32_e32 v85, v5
	v_exp_f32_e32 v86, v6
	v_exp_f32_e32 v87, v7
	v_exp_f32_e32 v88, v8
	v_exp_f32_e32 v89, v9
	v_exp_f32_e32 v90, v10
	v_exp_f32_e32 v91, v11
	v_exp_f32_e32 v92, v12
	v_exp_f32_e32 v93, v13
	v_exp_f32_e32 v94, v14
	v_exp_f32_e32 v95, v15
	v_exp_f32_e32 v96, v16
	v_exp_f32_e32 v97, v17
	v_subrev_u32_e32 v0, s78, v0
	v_mov_b32_e32 v14, v1
	v_mov_b32_e32 v15, v1
	v_add3_u32 v208, v36, v199, v201
	v_mul_f32_e32 v203, 0x3fb8aa3b, v34
	v_add_u32_e32 v179, s79, v0
	v_add_u32_e32 v209, s80, v0
	v_mov_b32_e32 v0, v1
	v_mov_b32_e32 v2, v1
	v_mov_b32_e32 v3, v1
	v_mov_b32_e32 v4, v1
	v_mov_b32_e32 v5, v1
	v_mov_b32_e32 v6, v1
	v_mov_b32_e32 v7, v1
	v_mov_b32_e32 v8, v1
	v_mov_b32_e32 v9, v1
	v_mov_b32_e32 v10, v1
	v_mov_b32_e32 v11, v1
	v_mov_b32_e32 v12, v1
	v_mov_b32_e32 v13, v1
	v_mov_b64_e32 v[64:65], v[14:15]
	v_mov_b64_e32 v[48:49], v[14:15]
	v_mov_b64_e32 v[32:33], v[14:15]
	v_mov_b64_e32 v[62:63], v[12:13]
	v_mov_b64_e32 v[60:61], v[10:11]
	v_mov_b64_e32 v[58:59], v[8:9]
	v_mov_b64_e32 v[56:57], v[6:7]
	v_mov_b64_e32 v[54:55], v[4:5]
	v_mov_b64_e32 v[52:53], v[2:3]
	v_mov_b64_e32 v[50:51], v[0:1]
	v_mov_b64_e32 v[46:47], v[12:13]
	v_mov_b64_e32 v[44:45], v[10:11]
	v_mov_b64_e32 v[42:43], v[8:9]
	v_mov_b64_e32 v[40:41], v[6:7]
	v_mov_b64_e32 v[38:39], v[4:5]
	v_mov_b64_e32 v[36:37], v[2:3]
	v_mov_b64_e32 v[34:35], v[0:1]
	v_mov_b64_e32 v[30:31], v[12:13]
	v_mov_b64_e32 v[28:29], v[10:11]
	v_mov_b64_e32 v[26:27], v[8:9]
	v_mov_b64_e32 v[24:25], v[6:7]
	v_mov_b64_e32 v[22:23], v[4:5]
	v_mov_b64_e32 v[20:21], v[2:3]
	v_mov_b64_e32 v[18:19], v[0:1]
	v_mov_b64_e32 v[16:17], v[14:15]
	s_mov_b32 s58, 4
	v_lshrrev_b32_e32 v193, 4, v197
	s_mov_b32 s44, 1
	v_and_b32_e32 v195, 15, v184
	s_mov_b32 s6, 0
	s_mov_b32 s51, 2
	s_sub_i32 s49, 0, s48
	s_sub_i32 s50, 0, s55
	v_mov_b32_e32 v178, 0
	s_movk_i32 s47, 0x4000
	s_mov_b64 s[40:41], 0
	s_mov_b32 s52, 0x8000
	v_mov_b64_e32 v[14:15], v[12:13]
	v_mov_b64_e32 v[12:13], v[10:11]
	v_mov_b64_e32 v[10:11], v[8:9]
	v_mov_b64_e32 v[8:9], v[6:7]
	v_mov_b64_e32 v[6:7], v[4:5]
	v_mov_b64_e32 v[4:5], v[2:3]
	v_mov_b64_e32 v[2:3], v[0:1]
	s_movk_i32 s61, 0x4000
	s_mov_b32 s45, 0x8000
.LBB0_1156:
	v_add_u32_e32 v0, s6, v208
	ds_read_b64_tr_b16 v[174:175], v0 offset:32768
	ds_read_b64_tr_b16 v[176:177], v0 offset:33280
	s_add_i32 s6, s47, 0xffffe000
	s_and_b32 s60, s6, 0x6000
	v_add_u32_e32 v130, s60, v205
	s_waitcnt lgkmcnt(2)
	v_mfma_f32_32x32x16_bf16 v[114:129], v[114:117], v[158:161], 0
	v_add_f32_e32 v98, v82, v83
	v_add_f32_e32 v98, v84, v98
	v_add_f32_e32 v98, v85, v98
	v_add_f32_e32 v98, v86, v98
	v_add_f32_e32 v98, v87, v98
	v_cvt_pk_bf16_f32 v142, v82, v83
	v_cvt_pk_bf16_f32 v143, v84, v85
	ds_read_b64_tr_b16 v[82:83], v0 offset:36864
	ds_read_b64_tr_b16 v[84:85], v0 offset:37376
	v_add_f32_e32 v98, v88, v98
	v_add_f32_e32 v98, v89, v98
	v_add_f32_e32 v98, v90, v98
	v_add_f32_e32 v131, v91, v98
	v_mfma_f32_32x32x16_bf16 v[98:113], v[170:173], v[158:161], 0
	v_cvt_pk_bf16_f32 v144, v86, v87
	v_cvt_pk_bf16_f32 v145, v88, v89
	ds_read_b128 v[170:173], v130 offset:4096
	ds_read_b128 v[210:213], v130 offset:4608
	ds_read_b64_tr_b16 v[86:87], v0 offset:33792
	ds_read_b64_tr_b16 v[88:89], v0 offset:34304
	v_mfma_f32_32x32x16_bf16 v[114:129], v[166:169], v[154:157], v[114:129]
	v_add_f32_e32 v131, v92, v131
	v_add_f32_e32 v131, v93, v131
	v_add_f32_e32 v131, v94, v131
	v_add_f32_e32 v131, v95, v131
	v_cvt_pk_bf16_f32 v138, v90, v91
	v_cvt_pk_bf16_f32 v139, v92, v93
	ds_read_b64_tr_b16 v[90:91], v0 offset:37888
	ds_read_b64_tr_b16 v[92:93], v0 offset:38400
	v_mfma_f32_32x32x16_bf16 v[98:113], v[162:165], v[154:157], v[98:113]
	v_add_f32_e32 v131, v96, v131
	v_add_f32_e32 v131, v97, v131
	v_add_f32_e32 v131, v66, v131
	v_add_f32_e32 v131, v67, v131
	v_cvt_pk_bf16_f32 v140, v94, v95
	v_cvt_pk_bf16_f32 v141, v96, v97
	ds_read_b128 v[162:165], v130 offset:6144
	ds_read_b128 v[166:169], v130 offset:6656
	ds_read_b64_tr_b16 v[94:95], v0 offset:34816
	ds_read_b64_tr_b16 v[96:97], v0 offset:35328
	s_waitcnt lgkmcnt(9)
	v_mfma_f32_32x32x16_bf16 v[114:129], v[170:173], v[150:153], v[114:129]
	v_add_f32_e32 v130, v68, v131
	v_add_f32_e32 v130, v69, v130
	v_add_f32_e32 v130, v70, v130
	v_add_f32_e32 v130, v71, v130
	v_cvt_pk_bf16_f32 v134, v66, v67
	v_cvt_pk_bf16_f32 v135, v68, v69
	ds_read_b64_tr_b16 v[66:67], v0 offset:38912
	ds_read_b64_tr_b16 v[68:69], v0 offset:39424
	s_waitcnt lgkmcnt(10)
	v_mfma_f32_32x32x16_bf16 v[98:113], v[210:213], v[150:153], v[98:113]
	v_add_f32_e32 v130, v72, v130
	v_add_f32_e32 v130, v73, v130
	v_add_f32_e32 v130, v74, v130
	v_add_f32_e32 v130, v75, v130
	v_cvt_pk_bf16_f32 v136, v70, v71
	v_cvt_pk_bf16_f32 v137, v72, v73
	ds_read_b64_tr_b16 v[70:71], v0 offset:35840
	ds_read_b64_tr_b16 v[72:73], v0 offset:36352
	s_waitcnt lgkmcnt(7)
	v_mfma_f32_32x32x16_bf16 v[114:129], v[162:165], v[146:149], v[114:129]
	v_add_f32_e32 v130, v76, v130
	v_add_f32_e32 v130, v77, v130
	v_add_f32_e32 v130, v78, v130
	v_add_f32_e32 v170, v79, v130
	v_cvt_pk_bf16_f32 v130, v74, v75
	v_cvt_pk_bf16_f32 v131, v76, v77
	ds_read_b64_tr_b16 v[74:75], v0 offset:39936
	ds_read_b64_tr_b16 v[76:77], v0 offset:40448
	s_waitcnt lgkmcnt(8)
	v_mfma_f32_32x32x16_bf16 v[98:113], v[166:169], v[146:149], v[98:113]
	v_add_f32_e32 v132, v80, v170
	v_add_f32_e32 v132, v81, v132
	v_add_f32_e32 v162, 0, v132
	v_cvt_pk_bf16_f32 v132, v78, v79
	v_cvt_pk_bf16_f32 v133, v80, v81
	s_add_u32 s77, s8, s40
	s_addc_u32 s78, s9, s41
	s_add_u32 s6, s77, 0x80000
	s_addc_u32 s7, s78, 0
	s_add_i32 s46, s47, 0x4000
	s_and_b32 s12, s46, 0x6000
	s_add_i32 s12, s12, s33
	s_add_u32 s75, s71, s40
	s_addc_u32 s76, s73, s41
	s_mov_b32 m0, s12
	s_nop 0
	global_load_lds_dwordx4 v206, s[6:7]
	s_add_u32 s6, s75, 0x22040000
	s_addc_u32 s7, s76, 0
	s_add_i32 s14, s45, s57
	s_mov_b32 m0, s14
	s_nop 0
	global_load_lds_dwordx4 v207, s[6:7]
	s_add_u32 s12, s75, 0x22040080
	s_addc_u32 s13, s76, 0
	s_addk_i32 s14, 0x2000
	s_cmp_ge_i32 s44, s55
	s_cselect_b64 s[82:83], -1, 0
	s_cmp_gt_i32 s56, s44
	s_cselect_b64 s[6:7], -1, 0
	s_mov_b32 m0, s14
	s_nop 0
	global_load_lds_dwordx4 v207, s[12:13]
	s_and_b64 s[82:83], s[82:83], s[6:7]
	s_andn2_b64 vcc, exec, s[82:83]
	s_cbranch_vccnz .LBB0_1158
	ds_read2_b32 v[78:79], v179 offset1:1
	ds_read2_b32 v[80:81], v179 offset0:2 offset1:3
	ds_read2_b32 v[164:165], v179 offset0:8 offset1:9
	ds_read2_b32 v[166:167], v179 offset0:10 offset1:11
	ds_read2_b32 v[168:169], v179 offset0:16 offset1:17
	ds_read2_b32 v[170:171], v179 offset0:18 offset1:19
	ds_read2_b32 v[172:173], v179 offset0:24 offset1:25
	ds_read2_b32 v[180:181], v179 offset0:26 offset1:27
	ds_read2_b32 v[210:211], v179 offset0:32 offset1:33
	ds_read2_b32 v[212:213], v179 offset0:34 offset1:35
	ds_read2_b32 v[214:215], v179 offset0:40 offset1:41
	ds_read2_b32 v[216:217], v179 offset0:42 offset1:43
	s_waitcnt lgkmcnt(11)
	v_pk_add_f32 v[114:115], v[114:115], v[78:79]
	s_waitcnt lgkmcnt(5)
	v_pk_add_f32 v[126:127], v[126:127], v[172:173]
	v_pk_add_f32 v[124:125], v[124:125], v[170:171]
	v_pk_add_f32 v[122:123], v[122:123], v[168:169]
	ds_read2_b32 v[78:79], v179 offset0:48 offset1:49
	ds_read2_b32 v[168:169], v179 offset0:50 offset1:51
	ds_read2_b32 v[170:171], v179 offset0:56 offset1:57
	ds_read2_b32 v[172:173], v179 offset0:58 offset1:59
	s_waitcnt lgkmcnt(8)
	v_pk_add_f32 v[128:129], v[128:129], v[180:181]
	v_pk_add_f32 v[120:121], v[120:121], v[166:167]
	v_pk_add_f32 v[118:119], v[118:119], v[164:165]
	v_pk_add_f32 v[116:117], v[116:117], v[80:81]
	s_waitcnt lgkmcnt(7)
	v_pk_add_f32 v[98:99], v[98:99], v[210:211]
	s_waitcnt lgkmcnt(0)
	v_pk_add_f32 v[112:113], v[112:113], v[172:173]
	v_pk_add_f32 v[110:111], v[110:111], v[170:171]
	v_pk_add_f32 v[108:109], v[108:109], v[168:169]
	v_pk_add_f32 v[106:107], v[106:107], v[78:79]
	v_pk_add_f32 v[104:105], v[104:105], v[216:217]
	v_pk_add_f32 v[102:103], v[102:103], v[214:215]
	v_pk_add_f32 v[100:101], v[100:101], v[212:213]

.LBB0_1160:
	s_add_i32 s79, s44, 1
	s_add_i32 s6, s45, 0x4000
	s_cmpk_lg_u32 s45, 0x8000
	s_cselect_b32 s53, s6, 0
	v_add_u32_e32 v174, s61, v208
	ds_read_b64_tr_b16 v[170:171], v174 offset:32768
	ds_read_b64_tr_b16 v[172:173], v174 offset:33280
	s_waitcnt lgkmcnt(5)
	v_mfma_f32_32x32x16_bf16 v[82:97], v[70:73], v[158:161], 0
	v_add_f32_e32 v74, v114, v115
	v_add_f32_e32 v74, v116, v74
	v_add_f32_e32 v74, v117, v74
	v_add_f32_e32 v74, v118, v74
	v_add_f32_e32 v74, v119, v74
	v_cvt_pk_bf16_f32 v142, v114, v115
	v_cvt_pk_bf16_f32 v143, v116, v117
	ds_read_b64_tr_b16 v[114:115], v174 offset:36864
	ds_read_b64_tr_b16 v[116:117], v174 offset:37376
	v_add_f32_e32 v70, v120, v74
	v_add_f32_e32 v70, v121, v70
	v_add_f32_e32 v70, v122, v70
	v_add_f32_e32 v130, v123, v70
	s_waitcnt lgkmcnt(6)
	v_mfma_f32_32x32x16_bf16 v[66:81], v[66:69], v[158:161], 0
	v_cvt_pk_bf16_f32 v144, v118, v119
	v_cvt_pk_bf16_f32 v145, v120, v121
	ds_read_b128 v[210:213], v175 offset:4096
	ds_read_b128 v[214:217], v175 offset:4608
	ds_read_b64_tr_b16 v[118:119], v174 offset:33792
	ds_read_b64_tr_b16 v[120:121], v174 offset:34304
	s_waitcnt lgkmcnt(9)
	v_mfma_f32_32x32x16_bf16 v[82:97], v[166:169], v[154:157], v[82:97]
	v_add_f32_e32 v130, v124, v130
	v_add_f32_e32 v130, v125, v130
	v_add_f32_e32 v130, v126, v130
	v_add_f32_e32 v130, v127, v130
	v_cvt_pk_bf16_f32 v138, v122, v123
	v_cvt_pk_bf16_f32 v139, v124, v125
	ds_read_b64_tr_b16 v[122:123], v174 offset:37888
	ds_read_b64_tr_b16 v[124:125], v174 offset:38400
	s_waitcnt lgkmcnt(10)
	v_mfma_f32_32x32x16_bf16 v[66:81], v[162:165], v[154:157], v[66:81]
	v_add_f32_e32 v130, v128, v130
	v_add_f32_e32 v130, v129, v130
	v_add_f32_e32 v130, v98, v130
	v_add_f32_e32 v130, v99, v130
	v_cvt_pk_bf16_f32 v140, v126, v127
	v_cvt_pk_bf16_f32 v141, v128, v129
	ds_read_b128 v[162:165], v175 offset:6144
	ds_read_b128 v[166:169], v175 offset:6656
	ds_read_b64_tr_b16 v[126:127], v174 offset:34816
	ds_read_b64_tr_b16 v[128:129], v174 offset:35328
	s_waitcnt lgkmcnt(9)
	v_mfma_f32_32x32x16_bf16 v[82:97], v[210:213], v[150:153], v[82:97]
	v_add_f32_e32 v130, v100, v130
	v_add_f32_e32 v130, v101, v130
	v_add_f32_e32 v130, v102, v130
	v_add_f32_e32 v130, v103, v130
	v_cvt_pk_bf16_f32 v134, v98, v99
	v_cvt_pk_bf16_f32 v135, v100, v101
	ds_read_b64_tr_b16 v[98:99], v174 offset:38912
	ds_read_b64_tr_b16 v[100:101], v174 offset:39424
	s_waitcnt lgkmcnt(10)
	v_mfma_f32_32x32x16_bf16 v[66:81], v[214:217], v[150:153], v[66:81]
	v_add_f32_e32 v130, v104, v130
	v_add_f32_e32 v130, v105, v130
	v_add_f32_e32 v130, v106, v130
	v_add_f32_e32 v130, v107, v130
	v_cvt_pk_bf16_f32 v136, v102, v103
	v_cvt_pk_bf16_f32 v137, v104, v105
	ds_read_b64_tr_b16 v[102:103], v174 offset:35840
	ds_read_b64_tr_b16 v[104:105], v174 offset:36352
	s_waitcnt lgkmcnt(7)
	v_mfma_f32_32x32x16_bf16 v[82:97], v[162:165], v[146:149], v[82:97]
	v_add_f32_e32 v130, v108, v130
	v_add_f32_e32 v130, v109, v130
	v_add_f32_e32 v130, v110, v130
	v_add_f32_e32 v175, v111, v130
	v_cvt_pk_bf16_f32 v130, v106, v107
	v_cvt_pk_bf16_f32 v131, v108, v109
	ds_read_b64_tr_b16 v[106:107], v174 offset:39936
	ds_read_b64_tr_b16 v[108:109], v174 offset:40448
	s_waitcnt lgkmcnt(8)
	v_mfma_f32_32x32x16_bf16 v[66:81], v[166:169], v[146:149], v[66:81]
	v_add_f32_e32 v132, v112, v175
	v_add_f32_e32 v132, v113, v132
	v_add_f32_e32 v162, 0, v132
	v_cvt_pk_bf16_f32 v132, v110, v111
	v_cvt_pk_bf16_f32 v133, v112, v113
	s_add_u32 s6, s77, 0xa0000
	s_addc_u32 s7, s78, 0
	s_add_i32 s12, s60, s33
	s_mov_b32 m0, s12
	s_nop 0
	global_load_lds_dwordx4 v206, s[6:7]
	s_add_u32 s6, s75, 0x22060000
	s_addc_u32 s7, s76, 0
	s_add_i32 s14, s53, s57
	s_mov_b32 m0, s14
	s_nop 0
	global_load_lds_dwordx4 v207, s[6:7]
	s_add_u32 s12, s75, 0x22060080
	s_addc_u32 s13, s76, 0
	s_addk_i32 s14, 0x2000
	s_cmp_ge_i32 s79, s55
	s_cselect_b64 s[60:61], -1, 0
	s_cmp_lt_i32 s79, s48
	s_cselect_b64 s[6:7], -1, 0
	s_mov_b32 m0, s14
	s_nop 0
	global_load_lds_dwordx4 v207, s[12:13]
	s_and_b64 s[60:61], s[60:61], s[6:7]
	s_andn2_b64 vcc, exec, s[60:61]
	s_cbranch_vccnz .LBB0_1162
	ds_read2_b32 v[110:111], v179 offset0:64 offset1:65
	ds_read2_b32 v[112:113], v179 offset0:66 offset1:67
	ds_read2_b32 v[164:165], v179 offset0:72 offset1:73
	ds_read2_b32 v[166:167], v179 offset0:74 offset1:75
	ds_read2_b32 v[168:169], v179 offset0:80 offset1:81
	ds_read2_b32 v[176:177], v179 offset0:82 offset1:83
	ds_read2_b32 v[180:181], v179 offset0:88 offset1:89
	ds_read2_b32 v[210:211], v179 offset0:90 offset1:91
	ds_read2_b32 v[212:213], v179 offset0:96 offset1:97
	ds_read2_b32 v[214:215], v179 offset0:98 offset1:99
	ds_read2_b32 v[216:217], v179 offset0:104 offset1:105
	ds_read2_b32 v[218:219], v179 offset0:106 offset1:107
	s_waitcnt lgkmcnt(11)
	v_pk_add_f32 v[82:83], v[82:83], v[110:111]
	s_waitcnt lgkmcnt(5)
	v_pk_add_f32 v[94:95], v[94:95], v[180:181]
	v_pk_add_f32 v[92:93], v[92:93], v[176:177]
	v_pk_add_f32 v[90:91], v[90:91], v[168:169]
	ds_read2_b32 v[110:111], v179 offset0:112 offset1:113
	ds_read2_b32 v[168:169], v179 offset0:114 offset1:115
	ds_read2_b32 v[176:177], v179 offset0:120 offset1:121
	ds_read2_b32 v[180:181], v179 offset0:122 offset1:123
	s_waitcnt lgkmcnt(8)
	v_pk_add_f32 v[96:97], v[96:97], v[210:211]
	v_pk_add_f32 v[88:89], v[88:89], v[166:167]
	v_pk_add_f32 v[86:87], v[86:87], v[164:165]
	v_pk_add_f32 v[84:85], v[84:85], v[112:113]
	s_waitcnt lgkmcnt(7)
	v_pk_add_f32 v[66:67], v[66:67], v[212:213]
	s_waitcnt lgkmcnt(0)
	v_pk_add_f32 v[80:81], v[80:81], v[180:181]
	v_pk_add_f32 v[78:79], v[78:79], v[176:177]
	v_pk_add_f32 v[76:77], v[76:77], v[168:169]
	v_pk_add_f32 v[74:75], v[74:75], v[110:111]
	v_pk_add_f32 v[72:73], v[72:73], v[218:219]
	v_pk_add_f32 v[70:71], v[70:71], v[216:217]
	v_pk_add_f32 v[68:69], v[68:69], v[214:215]

.LBB0_1168:
	v_add_u32_e32 v179, s45, v208
	ds_read_b64_tr_b16 v[174:175], v179 offset:32768
	ds_read_b64_tr_b16 v[176:177], v179 offset:33280
	s_add_i32 s6, s52, 0xffffe000
	s_and_b32 s76, s6, 0x6000
	v_add_u32_e32 v0, s76, v205
	s_waitcnt lgkmcnt(5)
	v_mfma_f32_32x32x16_bf16 v[114:129], v[114:117], v[158:161], 0
	v_add_f32_e32 v98, v82, v83
	v_add_f32_e32 v98, v84, v98
	v_add_f32_e32 v98, v85, v98
	v_add_f32_e32 v98, v86, v98
	v_add_f32_e32 v98, v87, v98
	v_cvt_pk_bf16_f32 v142, v82, v83
	v_cvt_pk_bf16_f32 v143, v84, v85
	ds_read_b64_tr_b16 v[82:83], v179 offset:36864
	ds_read_b64_tr_b16 v[84:85], v179 offset:37376
	v_add_f32_e32 v98, v88, v98
	v_add_f32_e32 v98, v89, v98
	v_add_f32_e32 v98, v90, v98
	v_add_f32_e32 v130, v91, v98
	s_waitcnt lgkmcnt(6)
	v_mfma_f32_32x32x16_bf16 v[98:113], v[170:173], v[158:161], 0
	v_cvt_pk_bf16_f32 v144, v86, v87
	v_cvt_pk_bf16_f32 v145, v88, v89
	ds_read_b128 v[170:173], v0 offset:4096
	ds_read_b128 v[210:213], v0 offset:4608
	ds_read_b64_tr_b16 v[86:87], v179 offset:33792
	ds_read_b64_tr_b16 v[88:89], v179 offset:34304
	s_waitcnt lgkmcnt(9)
	v_mfma_f32_32x32x16_bf16 v[114:129], v[166:169], v[154:157], v[114:129]
	v_add_f32_e32 v130, v92, v130
	v_add_f32_e32 v130, v93, v130
	v_add_f32_e32 v130, v94, v130
	v_add_f32_e32 v130, v95, v130
	v_cvt_pk_bf16_f32 v138, v90, v91
	v_cvt_pk_bf16_f32 v139, v92, v93
	ds_read_b64_tr_b16 v[90:91], v179 offset:37888
	ds_read_b64_tr_b16 v[92:93], v179 offset:38400
	s_waitcnt lgkmcnt(10)
	v_mfma_f32_32x32x16_bf16 v[98:113], v[162:165], v[154:157], v[98:113]
	v_add_f32_e32 v130, v96, v130
	v_add_f32_e32 v130, v97, v130
	v_add_f32_e32 v130, v66, v130
	v_add_f32_e32 v130, v67, v130
	v_cvt_pk_bf16_f32 v140, v94, v95
	v_cvt_pk_bf16_f32 v141, v96, v97
	ds_read_b128 v[162:165], v0 offset:6144
	ds_read_b128 v[166:169], v0 offset:6656
	ds_read_b64_tr_b16 v[94:95], v179 offset:34816
	ds_read_b64_tr_b16 v[96:97], v179 offset:35328
	s_waitcnt lgkmcnt(9)
	v_mfma_f32_32x32x16_bf16 v[114:129], v[170:173], v[150:153], v[114:129]
	v_add_f32_e32 v0, v68, v130
	v_add_f32_e32 v0, v69, v0
	v_add_f32_e32 v0, v70, v0
	v_add_f32_e32 v0, v71, v0
	v_cvt_pk_bf16_f32 v134, v66, v67
	v_cvt_pk_bf16_f32 v135, v68, v69
	ds_read_b64_tr_b16 v[66:67], v179 offset:38912
	ds_read_b64_tr_b16 v[68:69], v179 offset:39424
	s_waitcnt lgkmcnt(10)
	v_mfma_f32_32x32x16_bf16 v[98:113], v[210:213], v[150:153], v[98:113]
	v_add_f32_e32 v0, v72, v0
	v_add_f32_e32 v0, v73, v0
	v_add_f32_e32 v0, v74, v0
	v_add_f32_e32 v0, v75, v0
	v_cvt_pk_bf16_f32 v136, v70, v71
	v_cvt_pk_bf16_f32 v137, v72, v73
	ds_read_b64_tr_b16 v[70:71], v179 offset:35840
	ds_read_b64_tr_b16 v[72:73], v179 offset:36352
	s_waitcnt lgkmcnt(7)
	v_mfma_f32_32x32x16_bf16 v[114:129], v[162:165], v[146:149], v[114:129]
	v_add_f32_e32 v0, v76, v0
	v_add_f32_e32 v0, v77, v0
	v_add_f32_e32 v0, v78, v0
	v_add_f32_e32 v0, v79, v0
	v_cvt_pk_bf16_f32 v130, v74, v75
	v_cvt_pk_bf16_f32 v131, v76, v77
	ds_read_b64_tr_b16 v[74:75], v179 offset:39936
	ds_read_b64_tr_b16 v[76:77], v179 offset:40448
	s_waitcnt lgkmcnt(8)
	v_mfma_f32_32x32x16_bf16 v[98:113], v[166:169], v[146:149], v[98:113]
	v_add_f32_e32 v0, v80, v0
	v_add_f32_e32 v0, v81, v0
	v_add_f32_e32 v0, 0, v0
	v_cvt_pk_bf16_f32 v132, v78, v79
	v_cvt_pk_bf16_f32 v133, v80, v81
	s_add_i32 s73, s58, 2
	s_cmp_ge_u32 s73, s69
	s_cselect_b64 s[40:41], -1, 0
	s_and_b64 vcc, exec, s[40:41]
	s_cbranch_vccnz .LBB0_1170
	s_add_i32 s6, s52, 0x4000
	s_and_b32 s6, s6, 0x6000
	s_add_i32 s12, s6, s33
	s_add_u32 s6, s60, s8
	s_addc_u32 s7, s61, s9
	s_add_u32 s6, s6, 0x80000
	s_addc_u32 s7, s7, 0
	s_mov_b32 m0, s12
	s_nop 0
	global_load_lds_dwordx4 v206, s[6:7]
.LBB0_1170:
	s_add_i32 s75, s58, -1
	s_add_u32 s79, s70, s8
	s_addc_u32 s80, s71, s9
	s_add_u32 s6, s79, 0x22040000
	s_addc_u32 s7, s80, 0
	s_add_i32 s14, s59, s57
	s_mov_b32 m0, s14
	s_nop 0
	global_load_lds_dwordx4 v207, s[6:7]
	s_add_u32 s12, s79, 0x22040080
	s_addc_u32 s13, s80, 0
	s_addk_i32 s14, 0x2000
	s_cmp_ge_i32 s75, s55
	s_cselect_b64 s[44:45], -1, 0
	s_cmp_lt_i32 s75, s48
	s_cselect_b64 s[6:7], -1, 0
	s_mov_b32 m0, s14
	s_nop 0
	global_load_lds_dwordx4 v207, s[12:13]
	s_and_b64 s[44:45], s[44:45], s[6:7]
	s_andn2_b64 vcc, exec, s[44:45]
	s_cbranch_vccnz .LBB0_1172
	ds_read2_b32 v[78:79], v209 offset1:1
	ds_read2_b32 v[80:81], v209 offset0:2 offset1:3
	ds_read2_b32 v[162:163], v209 offset0:8 offset1:9
	ds_read2_b32 v[164:165], v209 offset0:10 offset1:11
	ds_read2_b32 v[166:167], v209 offset0:16 offset1:17
	ds_read2_b32 v[168:169], v209 offset0:18 offset1:19
	ds_read2_b32 v[170:171], v209 offset0:24 offset1:25
	ds_read2_b32 v[172:173], v209 offset0:26 offset1:27
	ds_read2_b32 v[180:181], v209 offset0:32 offset1:33
	ds_read2_b32 v[210:211], v209 offset0:34 offset1:35
	ds_read2_b32 v[212:213], v209 offset0:40 offset1:41
	ds_read2_b32 v[214:215], v209 offset0:42 offset1:43
	s_waitcnt lgkmcnt(11)
	v_pk_add_f32 v[114:115], v[114:115], v[78:79]
	s_waitcnt lgkmcnt(5)
	v_pk_add_f32 v[126:127], v[126:127], v[170:171]
	v_pk_add_f32 v[124:125], v[124:125], v[168:169]
	v_pk_add_f32 v[122:123], v[122:123], v[166:167]
	ds_read2_b32 v[78:79], v209 offset0:48 offset1:49
	ds_read2_b32 v[166:167], v209 offset0:50 offset1:51
	ds_read2_b32 v[168:169], v209 offset0:56 offset1:57
	ds_read2_b32 v[170:171], v209 offset0:58 offset1:59
	s_waitcnt lgkmcnt(8)
	v_pk_add_f32 v[128:129], v[128:129], v[172:173]
	v_pk_add_f32 v[120:121], v[120:121], v[164:165]
	v_pk_add_f32 v[118:119], v[118:119], v[162:163]
	v_pk_add_f32 v[116:117], v[116:117], v[80:81]
	s_waitcnt lgkmcnt(7)
	v_pk_add_f32 v[98:99], v[98:99], v[180:181]
	s_waitcnt lgkmcnt(0)
	v_pk_add_f32 v[112:113], v[112:113], v[170:171]
	v_pk_add_f32 v[110:111], v[110:111], v[168:169]
	v_pk_add_f32 v[108:109], v[108:109], v[166:167]
	v_pk_add_f32 v[106:107], v[106:107], v[78:79]
	v_pk_add_f32 v[104:105], v[104:105], v[214:215]
	v_pk_add_f32 v[102:103], v[102:103], v[212:213]
	v_pk_add_f32 v[100:101], v[100:101], v[210:211]

.LBB0_1182:
	v_add_u32_e32 v212, s53, v208
	ds_read_b64_tr_b16 v[174:175], v212 offset:32768
	ds_read_b64_tr_b16 v[176:177], v212 offset:33280
	s_waitcnt lgkmcnt(5)
	v_mfma_f32_32x32x16_bf16 v[82:97], v[70:73], v[158:161], 0
	v_add_f32_e32 v74, v114, v115
	v_add_f32_e32 v74, v116, v74
	v_add_f32_e32 v74, v117, v74
	v_add_f32_e32 v74, v118, v74
	v_add_f32_e32 v74, v119, v74
	v_cvt_pk_bf16_f32 v142, v114, v115
	v_cvt_pk_bf16_f32 v143, v116, v117
	ds_read_b64_tr_b16 v[178:179], v212 offset:36864
	ds_read_b64_tr_b16 v[180:181], v212 offset:37376
	v_add_f32_e32 v70, v120, v74
	v_add_f32_e32 v70, v121, v70
	v_add_f32_e32 v70, v122, v70
	v_add_f32_e32 v130, v123, v70
	s_waitcnt lgkmcnt(6)
	v_mfma_f32_32x32x16_bf16 v[66:81], v[66:69], v[158:161], 0
	v_cvt_pk_bf16_f32 v144, v118, v119
	v_cvt_pk_bf16_f32 v145, v120, v121
	ds_read_b128 v[114:117], v211 offset:4096
	ds_read_b128 v[170:173], v211 offset:4608
	ds_read_b64_tr_b16 v[118:119], v212 offset:33792
	ds_read_b64_tr_b16 v[120:121], v212 offset:34304
	s_waitcnt lgkmcnt(9)
	v_mfma_f32_32x32x16_bf16 v[82:97], v[166:169], v[154:157], v[82:97]
	v_add_f32_e32 v130, v124, v130
	v_add_f32_e32 v130, v125, v130
	v_add_f32_e32 v130, v126, v130
	v_add_f32_e32 v130, v127, v130
	v_cvt_pk_bf16_f32 v138, v122, v123
	v_cvt_pk_bf16_f32 v139, v124, v125
	ds_read_b64_tr_b16 v[122:123], v212 offset:37888
	ds_read_b64_tr_b16 v[124:125], v212 offset:38400
	s_waitcnt lgkmcnt(10)
	v_mfma_f32_32x32x16_bf16 v[66:81], v[162:165], v[154:157], v[66:81]
	v_add_f32_e32 v130, v128, v130
	v_add_f32_e32 v130, v129, v130
	v_add_f32_e32 v130, v98, v130
	v_add_f32_e32 v130, v99, v130
	v_cvt_pk_bf16_f32 v140, v126, v127
	v_cvt_pk_bf16_f32 v141, v128, v129
	ds_read_b128 v[166:169], v211 offset:6144
	ds_read_b128 v[162:165], v211 offset:6656
	ds_read_b64_tr_b16 v[126:127], v212 offset:34816
	ds_read_b64_tr_b16 v[128:129], v212 offset:35328
	s_waitcnt lgkmcnt(9)
	v_mfma_f32_32x32x16_bf16 v[82:97], v[114:117], v[150:153], v[82:97]
	v_add_f32_e32 v130, v100, v130
	v_add_f32_e32 v130, v101, v130
	v_add_f32_e32 v130, v102, v130
	v_add_f32_e32 v130, v103, v130
	v_cvt_pk_bf16_f32 v134, v98, v99
	v_cvt_pk_bf16_f32 v135, v100, v101
	ds_read_b64_tr_b16 v[98:99], v212 offset:38912
	ds_read_b64_tr_b16 v[100:101], v212 offset:39424
	s_waitcnt lgkmcnt(10)
	v_mfma_f32_32x32x16_bf16 v[66:81], v[170:173], v[150:153], v[66:81]
	v_add_f32_e32 v130, v104, v130
	v_add_f32_e32 v130, v105, v130
	v_add_f32_e32 v130, v106, v130
	v_add_f32_e32 v130, v107, v130
	v_cvt_pk_bf16_f32 v136, v102, v103
	v_cvt_pk_bf16_f32 v137, v104, v105
	ds_read_b64_tr_b16 v[102:103], v212 offset:35840
	ds_read_b64_tr_b16 v[104:105], v212 offset:36352
	s_waitcnt lgkmcnt(7)
	v_mfma_f32_32x32x16_bf16 v[82:97], v[166:169], v[146:149], v[82:97]
	v_add_f32_e32 v130, v108, v130
	v_add_f32_e32 v130, v109, v130
	v_add_f32_e32 v130, v110, v130
	v_add_f32_e32 v211, v111, v130
	v_cvt_pk_bf16_f32 v130, v106, v107
	v_cvt_pk_bf16_f32 v131, v108, v109
	ds_read_b64_tr_b16 v[106:107], v212 offset:39936
	ds_read_b64_tr_b16 v[108:109], v212 offset:40448
	s_waitcnt lgkmcnt(8)
	v_mfma_f32_32x32x16_bf16 v[66:81], v[162:165], v[146:149], v[66:81]
	v_add_f32_e32 v132, v112, v211
	v_add_f32_e32 v132, v113, v132
	v_add_f32_e32 v211, 0, v132
	v_cvt_pk_bf16_f32 v132, v110, v111
	v_cvt_pk_bf16_f32 v133, v112, v113
	s_add_i32 s6, s58, 3
	s_cmp_ge_u32 s6, s69
	s_cselect_b64 s[44:45], -1, 0
	s_and_b64 vcc, exec, s[44:45]
	s_cbranch_vccnz .LBB0_1184
	s_add_i32 s12, s76, s33
	s_add_u32 s6, s60, s8
	s_addc_u32 s7, s61, s9
	s_add_u32 s6, s6, 0xa0000
	s_addc_u32 s7, s7, 0
	s_mov_b32 m0, s12
	s_nop 0
	global_load_lds_dwordx4 v206, s[6:7]
.LBB0_1184:
	s_add_i32 s6, s59, 0x4000
	s_cmpk_lg_u32 s59, 0x8000
	s_cselect_b32 s53, s6, 0
	s_add_i32 s6, s58, 1
	s_cmp_lt_u32 s6, s69
	s_cselect_b64 s[46:47], -1, 0
	s_cmp_ge_u32 s6, s69
	s_cbranch_scc1 .LBB0_1186
	s_add_u32 s6, s79, 0x22060000
	s_addc_u32 s7, s80, 0
	s_add_u32 s12, s79, 0x22060080
	s_addc_u32 s13, s80, 0
	s_add_i32 s14, s53, s57
	s_mov_b32 m0, s14
	s_nop 0
	global_load_lds_dwordx4 v207, s[6:7]
	s_add_i32 s6, s14, 0x2000
	s_mov_b32 m0, s6
	s_nop 0
	global_load_lds_dwordx4 v207, s[12:13]
